# GEMM DMA loops: barrier moved to mid-stage, next-stage LDS fragment reads issued across it (software-pipelined ds_reads), DMA issue in second half
# baseline (speedup 1.0000x reference)
.LBB0_238:
	v_add_co_u32_e32 v182, vcc, 0x800, v154
	s_nop 1
	v_addc_co_u32_e32 v183, vcc, 0, v155, vcc
	v_add_co_u32_e32 v204, vcc, s34, v182
	s_nop 1
	v_addc_co_u32_e32 v205, vcc, 0, v183, vcc
	v_add_co_u32_e32 v206, vcc, s35, v182
	s_nop 1
	v_addc_co_u32_e32 v207, vcc, 0, v183, vcc
	v_mov_b32_e32 v208, v152
	v_mov_b32_e32 v209, v153
	v_add_co_u32_e32 v210, vcc, s30, v152
	s_nop 1
	v_addc_co_u32_e32 v211, vcc, 0, v153, vcc
	v_add_co_u32_e32 v212, vcc, s29, v152
	s_nop 1
	v_addc_co_u32_e32 v213, vcc, 0, v153, vcc
	v_add_co_u32_e32 v214, vcc, s31, v152
	s_nop 1
	v_addc_co_u32_e32 v215, vcc, 0, v153, vcc
	v_and_b32_e32 v216, 3, v156
	v_bfe_u32 v217, v156, 4, 2
	v_xor_b32_e32 v218, v216, v217
	v_sub_u32_e32 v218, v218, v216
	v_lshlrev_b32_e32 v218, 4, v218
	v_ashrrev_i32_e32 v219, 31, v218
	v_lshl_add_u64 v[204:205], v[218:219], 0, v[204:205]
	v_lshl_add_u64 v[206:207], v[218:219], 0, v[206:207]
	v_lshl_add_u64 v[208:209], v[218:219], 0, v[208:209]
	v_lshl_add_u64 v[210:211], v[218:219], 0, v[210:211]
	v_lshl_add_u64 v[212:213], v[218:219], 0, v[212:213]
	v_lshl_add_u64 v[214:215], v[218:219], 0, v[214:215]
	v_mov_b32_e32 v216, 64
	v_mov_b32_e32 v217, 0
	v_lshl_add_u64 v[204:205], v[216:217], 1, v[204:205]
	v_lshl_add_u64 v[206:207], v[216:217], 1, v[206:207]
	v_lshl_add_u64 v[208:209], v[216:217], 1, v[208:209]
	v_lshl_add_u64 v[210:211], v[216:217], 1, v[210:211]
	v_lshl_add_u64 v[212:213], v[216:217], 1, v[212:213]
	v_lshl_add_u64 v[214:215], v[216:217], 1, v[214:215]
	v_lshrrev_b32_e32 v246, 6, v156
	v_lshlrev_b32_e32 v246, 10, v246
	s_nop 0
	v_readfirstlane_b32 s4, v246
	ds_read_b128 v[162:165], v160 offset:8192
	ds_read_b128 v[178:181], v159
	ds_read_b128 v[166:169], v160 offset:10240
	ds_read_b128 v[200:203], v159 offset:2048
	ds_read_b128 v[170:173], v160 offset:12288
	ds_read_b128 v[174:177], v160 offset:14336
	s_waitcnt lgkmcnt(4)
	v_mfma_f32_32x32x16_bf16 v[112:127], v[162:165], v[178:181], v[112:127]
	s_waitcnt lgkmcnt(3)
	v_mfma_f32_32x32x16_bf16 v[96:111], v[166:169], v[178:181], v[96:111]
	s_waitcnt lgkmcnt(1)
	v_mfma_f32_32x32x16_bf16 v[48:63], v[170:173], v[178:181], v[48:63]
	s_waitcnt lgkmcnt(0)
	v_mfma_f32_32x32x16_bf16 v[32:47], v[174:177], v[178:181], v[32:47]
	v_mfma_f32_32x32x16_bf16 v[80:95], v[162:165], v[200:203], v[80:95]
	v_mfma_f32_32x32x16_bf16 v[64:79], v[166:169], v[200:203], v[64:79]
	v_mfma_f32_32x32x16_bf16 v[16:31], v[170:173], v[200:203], v[16:31]
	v_mfma_f32_32x32x16_bf16 v[0:15], v[174:177], v[200:203], v[0:15]
	ds_read_b128 v[162:165], v157 offset:8192
	ds_read_b128 v[178:181], v158
	ds_read_b128 v[166:169], v157 offset:10240
	ds_read_b128 v[200:203], v158 offset:2048
	ds_read_b128 v[170:173], v157 offset:12288
	ds_read_b128 v[174:177], v157 offset:14336
	s_waitcnt vmcnt(5)
	ds_write_b128 v161, v[140:143] offset:24576
	s_waitcnt vmcnt(3)
	ds_write_b128 v161, v[148:151] offset:28672
	ds_write_b128 v161, v[128:131] offset:32768
	s_waitcnt vmcnt(2)
	ds_write_b128 v161, v[136:139] offset:36864
	s_waitcnt vmcnt(1)
	ds_write_b128 v161, v[132:135] offset:40960
	s_waitcnt vmcnt(0)
	ds_write_b128 v161, v[144:147] offset:45056
	s_add_u32 m0, s4, 0xc000
	s_nop 0
	global_load_lds_dwordx4 v[204:205], off
	v_lshl_add_u64 v[204:205], v[216:217], 0, v[204:205]
	s_add_u32 m0, s4, 0xd000
	s_nop 0
	global_load_lds_dwordx4 v[206:207], off
	v_lshl_add_u64 v[206:207], v[216:217], 0, v[206:207]
	s_add_u32 m0, s4, 0xe000
	s_nop 0
	global_load_lds_dwordx4 v[208:209], off
	v_lshl_add_u64 v[208:209], v[216:217], 0, v[208:209]
	s_add_u32 m0, s4, 0xf000
	s_nop 0
	global_load_lds_dwordx4 v[210:211], off
	v_lshl_add_u64 v[210:211], v[216:217], 0, v[210:211]
	s_add_u32 m0, s4, 0x10000
	s_nop 0
	global_load_lds_dwordx4 v[212:213], off
	v_lshl_add_u64 v[212:213], v[216:217], 0, v[212:213]
	s_add_u32 m0, s4, 0x11000
	s_nop 0
	global_load_lds_dwordx4 v[214:215], off
	v_lshl_add_u64 v[214:215], v[216:217], 0, v[214:215]
	s_waitcnt lgkmcnt(10)
	v_mfma_f32_32x32x16_bf16 v[112:127], v[162:165], v[178:181], v[112:127]
	s_waitcnt lgkmcnt(9)
	v_mfma_f32_32x32x16_bf16 v[96:111], v[166:169], v[178:181], v[96:111]
	s_waitcnt lgkmcnt(7)
	v_mfma_f32_32x32x16_bf16 v[48:63], v[170:173], v[178:181], v[48:63]
	s_waitcnt lgkmcnt(6)
	v_mfma_f32_32x32x16_bf16 v[32:47], v[174:177], v[178:181], v[32:47]
	v_mfma_f32_32x32x16_bf16 v[80:95], v[162:165], v[200:203], v[80:95]
	v_mfma_f32_32x32x16_bf16 v[64:79], v[166:169], v[200:203], v[64:79]
	v_mfma_f32_32x32x16_bf16 v[16:31], v[170:173], v[200:203], v[16:31]
	v_mfma_f32_32x32x16_bf16 v[0:15], v[174:177], v[200:203], v[0:15]
	s_waitcnt lgkmcnt(0)
	s_barrier
	ds_read_b128 v[162:165], v160 offset:32768
	ds_read_b128 v[178:181], v159 offset:24576
	ds_read_b128 v[166:169], v160 offset:34816
	ds_read_b128 v[200:203], v159 offset:26624
	ds_read_b128 v[170:173], v160 offset:36864
	ds_read_b128 v[174:177], v160 offset:38912
	ds_read_b128 v[128:131], v157 offset:32768
	ds_read_b128 v[132:135], v158 offset:24576
	ds_read_b128 v[136:139], v157 offset:34816
	ds_read_b128 v[144:147], v158 offset:26624
	ds_read_b128 v[140:143], v157 offset:36864
	ds_read_b128 v[148:151], v157 offset:38912
	s_mov_b32 m0, s4
	s_nop 0
	global_load_lds_dwordx4 v[204:205], off
	v_lshl_add_u64 v[204:205], v[216:217], 0, v[204:205]
	s_add_u32 m0, s4, 0x1000
	s_nop 0
	global_load_lds_dwordx4 v[206:207], off
	v_lshl_add_u64 v[206:207], v[216:217], 0, v[206:207]
	s_add_u32 m0, s4, 0x2000
	s_nop 0
	global_load_lds_dwordx4 v[208:209], off
	v_lshl_add_u64 v[208:209], v[216:217], 0, v[208:209]
	s_add_u32 m0, s4, 0x3000
	s_nop 0
	global_load_lds_dwordx4 v[210:211], off
	v_lshl_add_u64 v[210:211], v[216:217], 0, v[210:211]
	s_add_u32 m0, s4, 0x4000
	s_nop 0
	global_load_lds_dwordx4 v[212:213], off
	v_lshl_add_u64 v[212:213], v[216:217], 0, v[212:213]
	s_add_u32 m0, s4, 0x5000
	s_nop 0
	global_load_lds_dwordx4 v[214:215], off
	v_lshl_add_u64 v[214:215], v[216:217], 0, v[214:215]
	s_mov_b32 s5, 0
.Lg1_dma_loop:
	s_waitcnt lgkmcnt(10)
	v_mfma_f32_32x32x16_bf16 v[112:127], v[162:165], v[178:181], v[112:127]
	s_waitcnt lgkmcnt(9)
	v_mfma_f32_32x32x16_bf16 v[96:111], v[166:169], v[178:181], v[96:111]
	s_waitcnt lgkmcnt(7)
	v_mfma_f32_32x32x16_bf16 v[48:63], v[170:173], v[178:181], v[48:63]
	s_waitcnt lgkmcnt(6)
	v_mfma_f32_32x32x16_bf16 v[32:47], v[174:177], v[178:181], v[32:47]
	v_mfma_f32_32x32x16_bf16 v[80:95], v[162:165], v[200:203], v[80:95]
	v_mfma_f32_32x32x16_bf16 v[64:79], v[166:169], v[200:203], v[64:79]
	v_mfma_f32_32x32x16_bf16 v[16:31], v[170:173], v[200:203], v[16:31]
	v_mfma_f32_32x32x16_bf16 v[0:15], v[174:177], v[200:203], v[0:15]
	s_waitcnt vmcnt(6)
	s_waitcnt lgkmcnt(0)
	s_barrier
	ds_read_b128 v[162:165], v160 offset:57344
	ds_read_b128 v[178:181], v159 offset:49152
	ds_read_b128 v[166:169], v160 offset:59392
	ds_read_b128 v[200:203], v159 offset:51200
	ds_read_b128 v[170:173], v160 offset:61440
	ds_read_b128 v[174:177], v160 offset:63488
	v_mfma_f32_32x32x16_bf16 v[112:127], v[128:131], v[132:135], v[112:127]
	s_add_u32 m0, s4, 0x6000
	s_nop 0
	global_load_lds_dwordx4 v[204:205], off
	v_lshl_add_u64 v[204:205], v[216:217], 0, v[204:205]
	v_mfma_f32_32x32x16_bf16 v[96:111], v[136:139], v[132:135], v[96:111]
	s_add_u32 m0, s4, 0x7000
	s_nop 0
	global_load_lds_dwordx4 v[206:207], off
	v_lshl_add_u64 v[206:207], v[216:217], 0, v[206:207]
	v_mfma_f32_32x32x16_bf16 v[48:63], v[140:143], v[132:135], v[48:63]
	s_add_u32 m0, s4, 0x8000
	s_nop 0
	global_load_lds_dwordx4 v[208:209], off
	v_lshl_add_u64 v[208:209], v[216:217], 0, v[208:209]
	v_mfma_f32_32x32x16_bf16 v[32:47], v[148:151], v[132:135], v[32:47]
	s_add_u32 m0, s4, 0x9000
	s_nop 0
	global_load_lds_dwordx4 v[210:211], off
	v_lshl_add_u64 v[210:211], v[216:217], 0, v[210:211]
	v_mfma_f32_32x32x16_bf16 v[80:95], v[128:131], v[144:147], v[80:95]
	s_add_u32 m0, s4, 0xa000
	s_nop 0
	global_load_lds_dwordx4 v[212:213], off
	v_lshl_add_u64 v[212:213], v[216:217], 0, v[212:213]
	v_mfma_f32_32x32x16_bf16 v[64:79], v[136:139], v[144:147], v[64:79]
	s_add_u32 m0, s4, 0xb000
	s_nop 0
	global_load_lds_dwordx4 v[214:215], off
	v_lshl_add_u64 v[214:215], v[216:217], 0, v[214:215]
	v_mfma_f32_32x32x16_bf16 v[16:31], v[140:143], v[144:147], v[16:31]
	v_mfma_f32_32x32x16_bf16 v[0:15], v[148:151], v[144:147], v[0:15]
	ds_read_b128 v[128:131], v157 offset:57344
	ds_read_b128 v[132:135], v158 offset:49152
	ds_read_b128 v[136:139], v157 offset:59392
	ds_read_b128 v[144:147], v158 offset:51200
	ds_read_b128 v[140:143], v157 offset:61440
	ds_read_b128 v[148:151], v157 offset:63488
	s_waitcnt lgkmcnt(10)
	v_mfma_f32_32x32x16_bf16 v[112:127], v[162:165], v[178:181], v[112:127]
	s_waitcnt lgkmcnt(9)
	v_mfma_f32_32x32x16_bf16 v[96:111], v[166:169], v[178:181], v[96:111]
	s_waitcnt lgkmcnt(7)
	v_mfma_f32_32x32x16_bf16 v[48:63], v[170:173], v[178:181], v[48:63]
	s_waitcnt lgkmcnt(6)
	v_mfma_f32_32x32x16_bf16 v[32:47], v[174:177], v[178:181], v[32:47]
	v_mfma_f32_32x32x16_bf16 v[80:95], v[162:165], v[200:203], v[80:95]
	v_mfma_f32_32x32x16_bf16 v[64:79], v[166:169], v[200:203], v[64:79]
	v_mfma_f32_32x32x16_bf16 v[16:31], v[170:173], v[200:203], v[16:31]
	v_mfma_f32_32x32x16_bf16 v[0:15], v[174:177], v[200:203], v[0:15]
	s_waitcnt vmcnt(6)
	s_waitcnt lgkmcnt(0)
	s_barrier
	ds_read_b128 v[162:165], v160 offset:8192
	ds_read_b128 v[178:181], v159
	ds_read_b128 v[166:169], v160 offset:10240
	ds_read_b128 v[200:203], v159 offset:2048
	ds_read_b128 v[170:173], v160 offset:12288
	ds_read_b128 v[174:177], v160 offset:14336
	v_mfma_f32_32x32x16_bf16 v[112:127], v[128:131], v[132:135], v[112:127]
	s_add_u32 m0, s4, 0xc000
	s_nop 0
	global_load_lds_dwordx4 v[204:205], off
	v_lshl_add_u64 v[204:205], v[216:217], 0, v[204:205]
	v_mfma_f32_32x32x16_bf16 v[96:111], v[136:139], v[132:135], v[96:111]
	s_add_u32 m0, s4, 0xd000
	s_nop 0
	global_load_lds_dwordx4 v[206:207], off
	v_lshl_add_u64 v[206:207], v[216:217], 0, v[206:207]
	v_mfma_f32_32x32x16_bf16 v[48:63], v[140:143], v[132:135], v[48:63]
	s_add_u32 m0, s4, 0xe000
	s_nop 0
	global_load_lds_dwordx4 v[208:209], off
	v_lshl_add_u64 v[208:209], v[216:217], 0, v[208:209]
	v_mfma_f32_32x32x16_bf16 v[32:47], v[148:151], v[132:135], v[32:47]
	s_add_u32 m0, s4, 0xf000
	s_nop 0
	global_load_lds_dwordx4 v[210:211], off
	v_lshl_add_u64 v[210:211], v[216:217], 0, v[210:211]
	v_mfma_f32_32x32x16_bf16 v[80:95], v[128:131], v[144:147], v[80:95]
	s_add_u32 m0, s4, 0x10000
	s_nop 0
	global_load_lds_dwordx4 v[212:213], off
	v_lshl_add_u64 v[212:213], v[216:217], 0, v[212:213]
	v_mfma_f32_32x32x16_bf16 v[64:79], v[136:139], v[144:147], v[64:79]
	s_add_u32 m0, s4, 0x11000
	s_nop 0
	global_load_lds_dwordx4 v[214:215], off
	v_lshl_add_u64 v[214:215], v[216:217], 0, v[214:215]
	v_mfma_f32_32x32x16_bf16 v[16:31], v[140:143], v[144:147], v[16:31]
	v_mfma_f32_32x32x16_bf16 v[0:15], v[148:151], v[144:147], v[0:15]
	ds_read_b128 v[128:131], v157 offset:8192
	ds_read_b128 v[132:135], v158
	ds_read_b128 v[136:139], v157 offset:10240
	ds_read_b128 v[144:147], v158 offset:2048
	ds_read_b128 v[140:143], v157 offset:12288
	ds_read_b128 v[148:151], v157 offset:14336
	s_waitcnt lgkmcnt(10)
	v_mfma_f32_32x32x16_bf16 v[112:127], v[162:165], v[178:181], v[112:127]
	s_waitcnt lgkmcnt(9)
	v_mfma_f32_32x32x16_bf16 v[96:111], v[166:169], v[178:181], v[96:111]
	s_waitcnt lgkmcnt(7)
	v_mfma_f32_32x32x16_bf16 v[48:63], v[170:173], v[178:181], v[48:63]
	s_waitcnt lgkmcnt(6)
	v_mfma_f32_32x32x16_bf16 v[32:47], v[174:177], v[178:181], v[32:47]
	v_mfma_f32_32x32x16_bf16 v[80:95], v[162:165], v[200:203], v[80:95]
	v_mfma_f32_32x32x16_bf16 v[64:79], v[166:169], v[200:203], v[64:79]
	v_mfma_f32_32x32x16_bf16 v[16:31], v[170:173], v[200:203], v[16:31]
	v_mfma_f32_32x32x16_bf16 v[0:15], v[174:177], v[200:203], v[0:15]
	s_waitcnt vmcnt(6)
	s_waitcnt lgkmcnt(0)
	s_barrier
	ds_read_b128 v[162:165], v160 offset:32768
	ds_read_b128 v[178:181], v159 offset:24576
	ds_read_b128 v[166:169], v160 offset:34816
	ds_read_b128 v[200:203], v159 offset:26624
	ds_read_b128 v[170:173], v160 offset:36864
	ds_read_b128 v[174:177], v160 offset:38912
	v_mfma_f32_32x32x16_bf16 v[112:127], v[128:131], v[132:135], v[112:127]
	s_mov_b32 m0, s4
	s_nop 0
	global_load_lds_dwordx4 v[204:205], off
	v_lshl_add_u64 v[204:205], v[216:217], 0, v[204:205]
	v_mfma_f32_32x32x16_bf16 v[96:111], v[136:139], v[132:135], v[96:111]
	s_add_u32 m0, s4, 0x1000
	s_nop 0
	global_load_lds_dwordx4 v[206:207], off
	v_lshl_add_u64 v[206:207], v[216:217], 0, v[206:207]
	v_mfma_f32_32x32x16_bf16 v[48:63], v[140:143], v[132:135], v[48:63]
	s_add_u32 m0, s4, 0x2000
	s_nop 0
	global_load_lds_dwordx4 v[208:209], off
	v_lshl_add_u64 v[208:209], v[216:217], 0, v[208:209]
	v_mfma_f32_32x32x16_bf16 v[32:47], v[148:151], v[132:135], v[32:47]
	s_add_u32 m0, s4, 0x3000
	s_nop 0
	global_load_lds_dwordx4 v[210:211], off
	v_lshl_add_u64 v[210:211], v[216:217], 0, v[210:211]
	v_mfma_f32_32x32x16_bf16 v[80:95], v[128:131], v[144:147], v[80:95]
	s_add_u32 m0, s4, 0x4000
	s_nop 0
	global_load_lds_dwordx4 v[212:213], off
	v_lshl_add_u64 v[212:213], v[216:217], 0, v[212:213]
	v_mfma_f32_32x32x16_bf16 v[64:79], v[136:139], v[144:147], v[64:79]
	s_add_u32 m0, s4, 0x5000
	s_nop 0
	global_load_lds_dwordx4 v[214:215], off
	v_lshl_add_u64 v[214:215], v[216:217], 0, v[214:215]
	v_mfma_f32_32x32x16_bf16 v[16:31], v[140:143], v[144:147], v[16:31]
	v_mfma_f32_32x32x16_bf16 v[0:15], v[148:151], v[144:147], v[0:15]
	ds_read_b128 v[128:131], v157 offset:32768
	ds_read_b128 v[132:135], v158 offset:24576
	ds_read_b128 v[136:139], v157 offset:34816
	ds_read_b128 v[144:147], v158 offset:26624
	ds_read_b128 v[140:143], v157 offset:36864
	ds_read_b128 v[148:151], v157 offset:38912
	s_add_u32 s5, s5, 1
	s_cmp_lg_u32 s5, 9
	s_cbranch_scc1 .Lg1_dma_loop
	s_waitcnt lgkmcnt(10)
	v_mfma_f32_32x32x16_bf16 v[112:127], v[162:165], v[178:181], v[112:127]
	s_waitcnt lgkmcnt(9)
	v_mfma_f32_32x32x16_bf16 v[96:111], v[166:169], v[178:181], v[96:111]
	s_waitcnt lgkmcnt(7)
	v_mfma_f32_32x32x16_bf16 v[48:63], v[170:173], v[178:181], v[48:63]
	s_waitcnt lgkmcnt(6)
	v_mfma_f32_32x32x16_bf16 v[32:47], v[174:177], v[178:181], v[32:47]
	v_mfma_f32_32x32x16_bf16 v[80:95], v[162:165], v[200:203], v[80:95]
	v_mfma_f32_32x32x16_bf16 v[64:79], v[166:169], v[200:203], v[64:79]
	v_mfma_f32_32x32x16_bf16 v[16:31], v[170:173], v[200:203], v[16:31]
	v_mfma_f32_32x32x16_bf16 v[0:15], v[174:177], v[200:203], v[0:15]
	s_waitcnt vmcnt(6)
	s_waitcnt lgkmcnt(0)
	s_barrier
	ds_read_b128 v[162:165], v160 offset:57344
	ds_read_b128 v[178:181], v159 offset:49152
	ds_read_b128 v[166:169], v160 offset:59392
	ds_read_b128 v[200:203], v159 offset:51200
	ds_read_b128 v[170:173], v160 offset:61440
	ds_read_b128 v[174:177], v160 offset:63488
	v_mfma_f32_32x32x16_bf16 v[112:127], v[128:131], v[132:135], v[112:127]
	s_add_u32 m0, s4, 0x6000
	s_nop 0
	global_load_lds_dwordx4 v[204:205], off
	v_lshl_add_u64 v[204:205], v[216:217], 0, v[204:205]
	v_mfma_f32_32x32x16_bf16 v[96:111], v[136:139], v[132:135], v[96:111]
	s_add_u32 m0, s4, 0x7000
	s_nop 0
	global_load_lds_dwordx4 v[206:207], off
	v_lshl_add_u64 v[206:207], v[216:217], 0, v[206:207]
	v_mfma_f32_32x32x16_bf16 v[48:63], v[140:143], v[132:135], v[48:63]
	s_add_u32 m0, s4, 0x8000
	s_nop 0
	global_load_lds_dwordx4 v[208:209], off
	v_lshl_add_u64 v[208:209], v[216:217], 0, v[208:209]
	v_mfma_f32_32x32x16_bf16 v[32:47], v[148:151], v[132:135], v[32:47]
	s_add_u32 m0, s4, 0x9000
	s_nop 0
	global_load_lds_dwordx4 v[210:211], off
	v_lshl_add_u64 v[210:211], v[216:217], 0, v[210:211]
	v_mfma_f32_32x32x16_bf16 v[80:95], v[128:131], v[144:147], v[80:95]
	s_add_u32 m0, s4, 0xa000
	s_nop 0
	global_load_lds_dwordx4 v[212:213], off
	v_lshl_add_u64 v[212:213], v[216:217], 0, v[212:213]
	v_mfma_f32_32x32x16_bf16 v[64:79], v[136:139], v[144:147], v[64:79]
	s_add_u32 m0, s4, 0xb000
	s_nop 0
	global_load_lds_dwordx4 v[214:215], off
	v_lshl_add_u64 v[214:215], v[216:217], 0, v[214:215]
	v_mfma_f32_32x32x16_bf16 v[16:31], v[140:143], v[144:147], v[16:31]
	v_mfma_f32_32x32x16_bf16 v[0:15], v[148:151], v[144:147], v[0:15]
	ds_read_b128 v[128:131], v157 offset:57344
	ds_read_b128 v[132:135], v158 offset:49152
	ds_read_b128 v[136:139], v157 offset:59392
	ds_read_b128 v[144:147], v158 offset:51200
	ds_read_b128 v[140:143], v157 offset:61440
	ds_read_b128 v[148:151], v157 offset:63488
	s_waitcnt lgkmcnt(10)
	v_mfma_f32_32x32x16_bf16 v[112:127], v[162:165], v[178:181], v[112:127]
	s_waitcnt lgkmcnt(9)
	v_mfma_f32_32x32x16_bf16 v[96:111], v[166:169], v[178:181], v[96:111]
	s_waitcnt lgkmcnt(7)
	v_mfma_f32_32x32x16_bf16 v[48:63], v[170:173], v[178:181], v[48:63]
	s_waitcnt lgkmcnt(6)
	v_mfma_f32_32x32x16_bf16 v[32:47], v[174:177], v[178:181], v[32:47]
	v_mfma_f32_32x32x16_bf16 v[80:95], v[162:165], v[200:203], v[80:95]
	v_mfma_f32_32x32x16_bf16 v[64:79], v[166:169], v[200:203], v[64:79]
	v_mfma_f32_32x32x16_bf16 v[16:31], v[170:173], v[200:203], v[16:31]
	v_mfma_f32_32x32x16_bf16 v[0:15], v[174:177], v[200:203], v[0:15]
	s_waitcnt vmcnt(6)
	s_waitcnt lgkmcnt(0)
	s_barrier
	ds_read_b128 v[162:165], v160 offset:8192
	ds_read_b128 v[178:181], v159
	ds_read_b128 v[166:169], v160 offset:10240
	ds_read_b128 v[200:203], v159 offset:2048
	ds_read_b128 v[170:173], v160 offset:12288
	ds_read_b128 v[174:177], v160 offset:14336
	v_mfma_f32_32x32x16_bf16 v[112:127], v[128:131], v[132:135], v[112:127]
	v_mfma_f32_32x32x16_bf16 v[96:111], v[136:139], v[132:135], v[96:111]
	v_mfma_f32_32x32x16_bf16 v[48:63], v[140:143], v[132:135], v[48:63]
	v_mfma_f32_32x32x16_bf16 v[32:47], v[148:151], v[132:135], v[32:47]
	v_mfma_f32_32x32x16_bf16 v[80:95], v[128:131], v[144:147], v[80:95]
	v_mfma_f32_32x32x16_bf16 v[64:79], v[136:139], v[144:147], v[64:79]
	v_mfma_f32_32x32x16_bf16 v[16:31], v[140:143], v[144:147], v[16:31]
	v_mfma_f32_32x32x16_bf16 v[0:15], v[148:151], v[144:147], v[0:15]
	ds_read_b128 v[128:131], v157 offset:8192
	ds_read_b128 v[132:135], v158
	ds_read_b128 v[136:139], v157 offset:10240
	ds_read_b128 v[144:147], v158 offset:2048
	ds_read_b128 v[140:143], v157 offset:12288
	ds_read_b128 v[148:151], v157 offset:14336
	s_waitcnt lgkmcnt(10)
	v_mfma_f32_32x32x16_bf16 v[112:127], v[162:165], v[178:181], v[112:127]
	s_waitcnt lgkmcnt(9)
	v_mfma_f32_32x32x16_bf16 v[96:111], v[166:169], v[178:181], v[96:111]
	s_waitcnt lgkmcnt(7)
	v_mfma_f32_32x32x16_bf16 v[48:63], v[170:173], v[178:181], v[48:63]
	s_waitcnt lgkmcnt(6)
	v_mfma_f32_32x32x16_bf16 v[32:47], v[174:177], v[178:181], v[32:47]
	v_mfma_f32_32x32x16_bf16 v[80:95], v[162:165], v[200:203], v[80:95]
	v_mfma_f32_32x32x16_bf16 v[64:79], v[166:169], v[200:203], v[64:79]
	v_mfma_f32_32x32x16_bf16 v[16:31], v[170:173], v[200:203], v[16:31]
	v_mfma_f32_32x32x16_bf16 v[0:15], v[174:177], v[200:203], v[0:15]
	s_waitcnt vmcnt(0)
	s_waitcnt lgkmcnt(0)
	s_barrier
	ds_read_b128 v[162:165], v160 offset:32768
	ds_read_b128 v[178:181], v159 offset:24576
	ds_read_b128 v[166:169], v160 offset:34816
	ds_read_b128 v[200:203], v159 offset:26624
	ds_read_b128 v[170:173], v160 offset:36864
	ds_read_b128 v[174:177], v160 offset:38912
	v_mfma_f32_32x32x16_bf16 v[112:127], v[128:131], v[132:135], v[112:127]
	v_mfma_f32_32x32x16_bf16 v[96:111], v[136:139], v[132:135], v[96:111]
	v_mfma_f32_32x32x16_bf16 v[48:63], v[140:143], v[132:135], v[48:63]
	v_mfma_f32_32x32x16_bf16 v[32:47], v[148:151], v[132:135], v[32:47]
	v_mfma_f32_32x32x16_bf16 v[80:95], v[128:131], v[144:147], v[80:95]
	v_mfma_f32_32x32x16_bf16 v[64:79], v[136:139], v[144:147], v[64:79]
	v_mfma_f32_32x32x16_bf16 v[16:31], v[140:143], v[144:147], v[16:31]
	v_mfma_f32_32x32x16_bf16 v[0:15], v[148:151], v[144:147], v[0:15]
	ds_read_b128 v[128:131], v157 offset:32768
	ds_read_b128 v[132:135], v158 offset:24576
	ds_read_b128 v[136:139], v157 offset:34816
	ds_read_b128 v[144:147], v158 offset:26624
	ds_read_b128 v[140:143], v157 offset:36864
	ds_read_b128 v[148:151], v157 offset:38912
	s_waitcnt lgkmcnt(10)
	v_mfma_f32_32x32x16_bf16 v[112:127], v[162:165], v[178:181], v[112:127]
	s_waitcnt lgkmcnt(9)
	v_mfma_f32_32x32x16_bf16 v[96:111], v[166:169], v[178:181], v[96:111]
	s_waitcnt lgkmcnt(7)
	v_mfma_f32_32x32x16_bf16 v[48:63], v[170:173], v[178:181], v[48:63]
	s_waitcnt lgkmcnt(6)
	v_mfma_f32_32x32x16_bf16 v[32:47], v[174:177], v[178:181], v[32:47]
	v_mfma_f32_32x32x16_bf16 v[80:95], v[162:165], v[200:203], v[80:95]
	v_mfma_f32_32x32x16_bf16 v[64:79], v[166:169], v[200:203], v[64:79]
	v_mfma_f32_32x32x16_bf16 v[16:31], v[170:173], v[200:203], v[16:31]
	v_mfma_f32_32x32x16_bf16 v[0:15], v[174:177], v[200:203], v[0:15]
	s_lshl_b32 s18, s18, 8
	s_movk_i32 s4, 0xec0
	s_cmpk_gt_u32 s18, 0x5ff
	s_cselect_b64 s[68:69], -1, 0
	s_cmpk_gt_u32 s18, 0x7ff
	s_cselect_b64 s[66:67], -1, 0
	s_cmpk_gt_u32 s18, 0x9ff
	s_cselect_b64 s[64:65], -1, 0
	v_and_b32_e32 v197, 31, v156
	v_bfe_u32 v195, v156, 5, 1
	v_lshlrev_b32_e32 v152, 1, v156
	v_and_b32_e32 v152, 0x80, v152
	v_or_b32_e32 v160, s18, v152
	v_cmp_gt_i32_e32 vcc, s4, v160
	s_movk_i32 s4, 0xe7f
	v_cmp_lt_u32_e64 s[62:63], s4, v160
	s_movk_i32 s4, 0xd7f
	v_cmp_lt_u32_e64 s[60:61], s4, v160
	s_movk_i32 s4, 0xd80
	v_cmp_gt_u32_e64 s[42:43], s4, v160
	v_readlane_b32 s4, v254, 28
	v_readlane_b32 s5, v254, 29
	s_nop 1
	v_cndmask_b32_e64 v190, 24, 0, s[42:43]
	v_mov_b32_e32 v161, v191
	v_lshl_add_u64 v[168:169], s[4:5], 0, v[190:191]
	v_cndmask_b32_e64 v164, v232, v233, s[42:43]
	v_ashrrev_i32_e32 v163, 31, v160
	v_mov_b32_e32 v162, v160
	s_cmpk_gt_u32 s18, 0xbff
	s_waitcnt lgkmcnt(0)
	s_barrier
	v_mfma_f32_32x32x16_bf16 v[112:127], v[128:131], v[132:135], v[112:127]
	v_mfma_f32_32x32x16_bf16 v[96:111], v[136:139], v[132:135], v[96:111]
	v_mfma_f32_32x32x16_bf16 v[48:63], v[140:143], v[132:135], v[48:63]
	v_mfma_f32_32x32x16_bf16 v[32:47], v[148:151], v[132:135], v[32:47]
	v_ashrrev_i32_e32 v132, 1, v156
	v_and_b32_e32 v132, 0xffffffc0, v132
	v_add_u32_e32 v199, s14, v132
	s_cselect_b64 s[14:15], -1, 0
	s_cmpk_gt_u32 s18, 0x6ff
	s_cselect_b64 s[4:5], -1, 0
	s_cmpk_lt_u32 s18, 0x700
	v_mfma_f32_32x32x16_bf16 v[80:95], v[128:131], v[144:147], v[80:95]
	v_cndmask_b32_e64 v128, v234, v235, s[42:43]
	v_mul_lo_u32 v166, v128, s2
	v_ashrrev_i32_e32 v167, 31, v166
	s_cselect_b64 s[18:19], -1, 0
	v_mfma_f32_32x32x16_bf16 v[64:79], v[136:139], v[144:147], v[64:79]
	v_mfma_f32_32x32x16_bf16 v[16:31], v[140:143], v[144:147], v[16:31]
	v_mfma_f32_32x32x16_bf16 v[0:15], v[148:151], v[144:147], v[0:15]
	s_and_saveexec_b64 s[56:57], vcc
	s_cbranch_execz .LBB0_377
	v_mov_b32_e32 v128, v197
	v_mov_b32_e32 v165, v195
	s_movk_i32 s20, 0x4000
	v_add_u32_e32 v178, v128, v199
	v_cmp_gt_i32_e64 s[54:55], s20, v178
	v_cmp_lt_i32_e64 s[52:53], s45, v178
	s_and_saveexec_b64 s[20:21], s[52:53]
	s_xor_b64 s[20:21], exec, s[20:21]
	v_add_u32_e32 v128, 0xffffc000, v178
	v_lshrrev_b32_e32 v182, 8, v128
	v_and_b32_e32 v180, 0xff, v178
	v_add_u32_e32 v140, 0x800, v178
	s_or_saveexec_b64 s[20:21], s[20:21]
	v_mov_b64_e32 v[200:201], 0
	s_xor_b64 exec, exec, s[20:21]
	s_cbranch_execz .LBB0_244
	v_readlane_b32 s22, v255, 48
	v_and_b32_e32 v180, 0xfff, v178
	v_ashrrev_i32_e32 v200, 12, v178
	v_add_u32_e32 v128, s22, v178
	s_movk_i32 s22, 0x1200
	v_ashrrev_i32_e32 v182, 12, v128
	v_mad_i32_i24 v140, v200, s22, v180
	v_ashrrev_i32_e32 v201, 31, v200

.LBB0_927:
	v_add_co_u32_e32 v182, vcc, 0x800, v152
	s_nop 1
	v_addc_co_u32_e32 v183, vcc, 0, v153, vcc
	v_add_co_u32_e32 v204, vcc, s95, v182
	s_nop 1
	v_addc_co_u32_e32 v205, vcc, 0, v183, vcc
	v_add_co_u32_e32 v206, vcc, s96, v182
	s_nop 1
	v_addc_co_u32_e32 v207, vcc, 0, v183, vcc
	v_add_co_u32_e32 v208, vcc, s97, v154
	s_nop 1
	v_addc_co_u32_e32 v209, vcc, 0, v155, vcc
	v_add_co_u32_e32 v210, vcc, s10, v154
	s_nop 1
	v_addc_co_u32_e32 v211, vcc, 0, v155, vcc
	v_add_co_u32_e32 v212, vcc, 0x1322000, v154
	s_nop 1
	v_addc_co_u32_e32 v213, vcc, 0, v155, vcc
	v_add_co_u32_e32 v214, vcc, 0x1344000, v154
	s_nop 1
	v_addc_co_u32_e32 v215, vcc, 0, v155, vcc
	v_and_b32_e32 v216, 3, v156
	v_bfe_u32 v217, v156, 4, 2
	v_xor_b32_e32 v218, v216, v217
	v_sub_u32_e32 v218, v218, v216
	v_lshlrev_b32_e32 v218, 4, v218
	v_ashrrev_i32_e32 v219, 31, v218
	v_lshl_add_u64 v[204:205], v[218:219], 0, v[204:205]
	v_lshl_add_u64 v[206:207], v[218:219], 0, v[206:207]
	v_lshl_add_u64 v[208:209], v[218:219], 0, v[208:209]
	v_lshl_add_u64 v[210:211], v[218:219], 0, v[210:211]
	v_lshl_add_u64 v[212:213], v[218:219], 0, v[212:213]
	v_lshl_add_u64 v[214:215], v[218:219], 0, v[214:215]
	v_mov_b32_e32 v216, 64
	v_mov_b32_e32 v217, 0
	v_lshl_add_u64 v[204:205], v[216:217], 1, v[204:205]
	v_lshl_add_u64 v[206:207], v[216:217], 1, v[206:207]
	v_lshl_add_u64 v[208:209], v[216:217], 1, v[208:209]
	v_lshl_add_u64 v[210:211], v[216:217], 1, v[210:211]
	v_lshl_add_u64 v[212:213], v[216:217], 1, v[212:213]
	v_lshl_add_u64 v[214:215], v[216:217], 1, v[214:215]
	v_lshrrev_b32_e32 v246, 6, v156
	v_lshlrev_b32_e32 v246, 10, v246
	s_nop 0
	v_readfirstlane_b32 s20, v246
	ds_read_b128 v[162:165], v157 offset:8192
	ds_read_b128 v[178:181], v161
	ds_read_b128 v[166:169], v157 offset:10240
	ds_read_b128 v[200:203], v161 offset:2048
	ds_read_b128 v[170:173], v157 offset:12288
	ds_read_b128 v[174:177], v157 offset:14336
	s_waitcnt lgkmcnt(4)
	v_mfma_f32_32x32x16_bf16 v[112:127], v[162:165], v[178:181], v[112:127]
	s_waitcnt lgkmcnt(3)
	v_mfma_f32_32x32x16_bf16 v[96:111], v[166:169], v[178:181], v[96:111]
	s_waitcnt lgkmcnt(1)
	v_mfma_f32_32x32x16_bf16 v[80:95], v[170:173], v[178:181], v[80:95]
	s_waitcnt lgkmcnt(0)
	v_mfma_f32_32x32x16_bf16 v[64:79], v[174:177], v[178:181], v[64:79]
	v_mfma_f32_32x32x16_bf16 v[48:63], v[162:165], v[200:203], v[48:63]
	v_mfma_f32_32x32x16_bf16 v[32:47], v[166:169], v[200:203], v[32:47]
	v_mfma_f32_32x32x16_bf16 v[16:31], v[170:173], v[200:203], v[16:31]
	v_mfma_f32_32x32x16_bf16 v[0:15], v[174:177], v[200:203], v[0:15]
	ds_read_b128 v[162:165], v159 offset:8192
	ds_read_b128 v[178:181], v158
	ds_read_b128 v[166:169], v159 offset:10240
	ds_read_b128 v[200:203], v158 offset:2048
	ds_read_b128 v[170:173], v159 offset:12288
	ds_read_b128 v[174:177], v159 offset:14336
	s_waitcnt vmcnt(5)
	ds_write_b128 v160, v[144:147] offset:24576
	s_waitcnt vmcnt(4)
	ds_write_b128 v160, v[148:151] offset:28672
	s_waitcnt vmcnt(3)
	ds_write_b128 v160, v[140:143] offset:32768
	s_waitcnt vmcnt(2)
	ds_write_b128 v160, v[136:139] offset:36864
	s_waitcnt vmcnt(1)
	ds_write_b128 v160, v[132:135] offset:40960
	s_waitcnt vmcnt(0)
	ds_write_b128 v160, v[128:131] offset:45056
	s_add_u32 m0, s20, 0xc000
	s_nop 0
	global_load_lds_dwordx4 v[204:205], off
	v_lshl_add_u64 v[204:205], v[216:217], 0, v[204:205]
	s_add_u32 m0, s20, 0xd000
	s_nop 0
	global_load_lds_dwordx4 v[206:207], off
	v_lshl_add_u64 v[206:207], v[216:217], 0, v[206:207]
	s_add_u32 m0, s20, 0xe000
	s_nop 0
	global_load_lds_dwordx4 v[208:209], off
	v_lshl_add_u64 v[208:209], v[216:217], 0, v[208:209]
	s_add_u32 m0, s20, 0xf000
	s_nop 0
	global_load_lds_dwordx4 v[210:211], off
	v_lshl_add_u64 v[210:211], v[216:217], 0, v[210:211]
	s_add_u32 m0, s20, 0x10000
	s_nop 0
	global_load_lds_dwordx4 v[212:213], off
	v_lshl_add_u64 v[212:213], v[216:217], 0, v[212:213]
	s_add_u32 m0, s20, 0x11000
	s_nop 0
	global_load_lds_dwordx4 v[214:215], off
	v_lshl_add_u64 v[214:215], v[216:217], 0, v[214:215]
	s_waitcnt lgkmcnt(10)
	v_mfma_f32_32x32x16_bf16 v[112:127], v[162:165], v[178:181], v[112:127]
	s_waitcnt lgkmcnt(9)
	v_mfma_f32_32x32x16_bf16 v[96:111], v[166:169], v[178:181], v[96:111]
	s_waitcnt lgkmcnt(7)
	v_mfma_f32_32x32x16_bf16 v[80:95], v[170:173], v[178:181], v[80:95]
	s_waitcnt lgkmcnt(6)
	v_mfma_f32_32x32x16_bf16 v[64:79], v[174:177], v[178:181], v[64:79]
	v_mfma_f32_32x32x16_bf16 v[48:63], v[162:165], v[200:203], v[48:63]
	v_mfma_f32_32x32x16_bf16 v[32:47], v[166:169], v[200:203], v[32:47]
	v_mfma_f32_32x32x16_bf16 v[16:31], v[170:173], v[200:203], v[16:31]
	v_mfma_f32_32x32x16_bf16 v[0:15], v[174:177], v[200:203], v[0:15]
	s_waitcnt lgkmcnt(0)
	s_barrier
	ds_read_b128 v[162:165], v157 offset:32768
	ds_read_b128 v[178:181], v161 offset:24576
	ds_read_b128 v[166:169], v157 offset:34816
	ds_read_b128 v[200:203], v161 offset:26624
	ds_read_b128 v[170:173], v157 offset:36864
	ds_read_b128 v[174:177], v157 offset:38912
	ds_read_b128 v[128:131], v159 offset:32768
	ds_read_b128 v[148:151], v158 offset:24576
	ds_read_b128 v[136:139], v159 offset:34816
	ds_read_b128 v[132:135], v158 offset:26624
	ds_read_b128 v[140:143], v159 offset:36864
	ds_read_b128 v[144:147], v159 offset:38912
	s_mov_b32 m0, s20
	s_nop 0
	global_load_lds_dwordx4 v[204:205], off
	v_lshl_add_u64 v[204:205], v[216:217], 0, v[204:205]
	s_add_u32 m0, s20, 0x1000
	s_nop 0
	global_load_lds_dwordx4 v[206:207], off
	v_lshl_add_u64 v[206:207], v[216:217], 0, v[206:207]
	s_add_u32 m0, s20, 0x2000
	s_nop 0
	global_load_lds_dwordx4 v[208:209], off
	v_lshl_add_u64 v[208:209], v[216:217], 0, v[208:209]
	s_add_u32 m0, s20, 0x3000
	s_nop 0
	global_load_lds_dwordx4 v[210:211], off
	v_lshl_add_u64 v[210:211], v[216:217], 0, v[210:211]
	s_add_u32 m0, s20, 0x4000
	s_nop 0
	global_load_lds_dwordx4 v[212:213], off
	v_lshl_add_u64 v[212:213], v[216:217], 0, v[212:213]
	s_add_u32 m0, s20, 0x5000
	s_nop 0
	global_load_lds_dwordx4 v[214:215], off
	v_lshl_add_u64 v[214:215], v[216:217], 0, v[214:215]
	s_mov_b32 s18, 0
.Lr0_dma_loop:
	s_waitcnt lgkmcnt(10)
	v_mfma_f32_32x32x16_bf16 v[112:127], v[162:165], v[178:181], v[112:127]
	s_waitcnt lgkmcnt(9)
	v_mfma_f32_32x32x16_bf16 v[96:111], v[166:169], v[178:181], v[96:111]
	s_waitcnt lgkmcnt(7)
	v_mfma_f32_32x32x16_bf16 v[80:95], v[170:173], v[178:181], v[80:95]
	s_waitcnt lgkmcnt(6)
	v_mfma_f32_32x32x16_bf16 v[64:79], v[174:177], v[178:181], v[64:79]
	v_mfma_f32_32x32x16_bf16 v[48:63], v[162:165], v[200:203], v[48:63]
	v_mfma_f32_32x32x16_bf16 v[32:47], v[166:169], v[200:203], v[32:47]
	v_mfma_f32_32x32x16_bf16 v[16:31], v[170:173], v[200:203], v[16:31]
	v_mfma_f32_32x32x16_bf16 v[0:15], v[174:177], v[200:203], v[0:15]
	s_waitcnt vmcnt(6)
	s_waitcnt lgkmcnt(0)
	s_barrier
	ds_read_b128 v[162:165], v157 offset:57344
	ds_read_b128 v[178:181], v161 offset:49152
	ds_read_b128 v[166:169], v157 offset:59392
	ds_read_b128 v[200:203], v161 offset:51200
	ds_read_b128 v[170:173], v157 offset:61440
	ds_read_b128 v[174:177], v157 offset:63488
	v_mfma_f32_32x32x16_bf16 v[112:127], v[128:131], v[148:151], v[112:127]
	s_add_u32 m0, s20, 0x6000
	s_nop 0
	global_load_lds_dwordx4 v[204:205], off
	v_lshl_add_u64 v[204:205], v[216:217], 0, v[204:205]
	v_mfma_f32_32x32x16_bf16 v[96:111], v[136:139], v[148:151], v[96:111]
	s_add_u32 m0, s20, 0x7000
	s_nop 0
	global_load_lds_dwordx4 v[206:207], off
	v_lshl_add_u64 v[206:207], v[216:217], 0, v[206:207]
	v_mfma_f32_32x32x16_bf16 v[80:95], v[140:143], v[148:151], v[80:95]
	s_add_u32 m0, s20, 0x8000
	s_nop 0
	global_load_lds_dwordx4 v[208:209], off
	v_lshl_add_u64 v[208:209], v[216:217], 0, v[208:209]
	v_mfma_f32_32x32x16_bf16 v[64:79], v[144:147], v[148:151], v[64:79]
	s_add_u32 m0, s20, 0x9000
	s_nop 0
	global_load_lds_dwordx4 v[210:211], off
	v_lshl_add_u64 v[210:211], v[216:217], 0, v[210:211]
	v_mfma_f32_32x32x16_bf16 v[48:63], v[128:131], v[132:135], v[48:63]
	s_add_u32 m0, s20, 0xa000
	s_nop 0
	global_load_lds_dwordx4 v[212:213], off
	v_lshl_add_u64 v[212:213], v[216:217], 0, v[212:213]
	v_mfma_f32_32x32x16_bf16 v[32:47], v[136:139], v[132:135], v[32:47]
	s_add_u32 m0, s20, 0xb000
	s_nop 0
	global_load_lds_dwordx4 v[214:215], off
	v_lshl_add_u64 v[214:215], v[216:217], 0, v[214:215]
	v_mfma_f32_32x32x16_bf16 v[16:31], v[140:143], v[132:135], v[16:31]
	v_mfma_f32_32x32x16_bf16 v[0:15], v[144:147], v[132:135], v[0:15]
	ds_read_b128 v[128:131], v159 offset:57344
	ds_read_b128 v[148:151], v158 offset:49152
	ds_read_b128 v[136:139], v159 offset:59392
	ds_read_b128 v[132:135], v158 offset:51200
	ds_read_b128 v[140:143], v159 offset:61440
	ds_read_b128 v[144:147], v159 offset:63488
	s_waitcnt lgkmcnt(10)
	v_mfma_f32_32x32x16_bf16 v[112:127], v[162:165], v[178:181], v[112:127]
	s_waitcnt lgkmcnt(9)
	v_mfma_f32_32x32x16_bf16 v[96:111], v[166:169], v[178:181], v[96:111]
	s_waitcnt lgkmcnt(7)
	v_mfma_f32_32x32x16_bf16 v[80:95], v[170:173], v[178:181], v[80:95]
	s_waitcnt lgkmcnt(6)
	v_mfma_f32_32x32x16_bf16 v[64:79], v[174:177], v[178:181], v[64:79]
	v_mfma_f32_32x32x16_bf16 v[48:63], v[162:165], v[200:203], v[48:63]
	v_mfma_f32_32x32x16_bf16 v[32:47], v[166:169], v[200:203], v[32:47]
	v_mfma_f32_32x32x16_bf16 v[16:31], v[170:173], v[200:203], v[16:31]
	v_mfma_f32_32x32x16_bf16 v[0:15], v[174:177], v[200:203], v[0:15]
	s_waitcnt vmcnt(6)
	s_waitcnt lgkmcnt(0)
	s_barrier
	ds_read_b128 v[162:165], v157 offset:8192
	ds_read_b128 v[178:181], v161
	ds_read_b128 v[166:169], v157 offset:10240
	ds_read_b128 v[200:203], v161 offset:2048
	ds_read_b128 v[170:173], v157 offset:12288
	ds_read_b128 v[174:177], v157 offset:14336
	v_mfma_f32_32x32x16_bf16 v[112:127], v[128:131], v[148:151], v[112:127]
	s_add_u32 m0, s20, 0xc000
	s_nop 0
	global_load_lds_dwordx4 v[204:205], off
	v_lshl_add_u64 v[204:205], v[216:217], 0, v[204:205]
	v_mfma_f32_32x32x16_bf16 v[96:111], v[136:139], v[148:151], v[96:111]
	s_add_u32 m0, s20, 0xd000
	s_nop 0
	global_load_lds_dwordx4 v[206:207], off
	v_lshl_add_u64 v[206:207], v[216:217], 0, v[206:207]
	v_mfma_f32_32x32x16_bf16 v[80:95], v[140:143], v[148:151], v[80:95]
	s_add_u32 m0, s20, 0xe000
	s_nop 0
	global_load_lds_dwordx4 v[208:209], off
	v_lshl_add_u64 v[208:209], v[216:217], 0, v[208:209]
	v_mfma_f32_32x32x16_bf16 v[64:79], v[144:147], v[148:151], v[64:79]
	s_add_u32 m0, s20, 0xf000
	s_nop 0
	global_load_lds_dwordx4 v[210:211], off
	v_lshl_add_u64 v[210:211], v[216:217], 0, v[210:211]
	v_mfma_f32_32x32x16_bf16 v[48:63], v[128:131], v[132:135], v[48:63]
	s_add_u32 m0, s20, 0x10000
	s_nop 0
	global_load_lds_dwordx4 v[212:213], off
	v_lshl_add_u64 v[212:213], v[216:217], 0, v[212:213]
	v_mfma_f32_32x32x16_bf16 v[32:47], v[136:139], v[132:135], v[32:47]
	s_add_u32 m0, s20, 0x11000
	s_nop 0
	global_load_lds_dwordx4 v[214:215], off
	v_lshl_add_u64 v[214:215], v[216:217], 0, v[214:215]
	v_mfma_f32_32x32x16_bf16 v[16:31], v[140:143], v[132:135], v[16:31]
	v_mfma_f32_32x32x16_bf16 v[0:15], v[144:147], v[132:135], v[0:15]
	ds_read_b128 v[128:131], v159 offset:8192
	ds_read_b128 v[148:151], v158
	ds_read_b128 v[136:139], v159 offset:10240
	ds_read_b128 v[132:135], v158 offset:2048
	ds_read_b128 v[140:143], v159 offset:12288
	ds_read_b128 v[144:147], v159 offset:14336
	s_waitcnt lgkmcnt(10)
	v_mfma_f32_32x32x16_bf16 v[112:127], v[162:165], v[178:181], v[112:127]
	s_waitcnt lgkmcnt(9)
	v_mfma_f32_32x32x16_bf16 v[96:111], v[166:169], v[178:181], v[96:111]
	s_waitcnt lgkmcnt(7)
	v_mfma_f32_32x32x16_bf16 v[80:95], v[170:173], v[178:181], v[80:95]
	s_waitcnt lgkmcnt(6)
	v_mfma_f32_32x32x16_bf16 v[64:79], v[174:177], v[178:181], v[64:79]
	v_mfma_f32_32x32x16_bf16 v[48:63], v[162:165], v[200:203], v[48:63]
	v_mfma_f32_32x32x16_bf16 v[32:47], v[166:169], v[200:203], v[32:47]
	v_mfma_f32_32x32x16_bf16 v[16:31], v[170:173], v[200:203], v[16:31]
	v_mfma_f32_32x32x16_bf16 v[0:15], v[174:177], v[200:203], v[0:15]
	s_waitcnt vmcnt(6)
	s_waitcnt lgkmcnt(0)
	s_barrier
	ds_read_b128 v[162:165], v157 offset:32768
	ds_read_b128 v[178:181], v161 offset:24576
	ds_read_b128 v[166:169], v157 offset:34816
	ds_read_b128 v[200:203], v161 offset:26624
	ds_read_b128 v[170:173], v157 offset:36864
	ds_read_b128 v[174:177], v157 offset:38912
	v_mfma_f32_32x32x16_bf16 v[112:127], v[128:131], v[148:151], v[112:127]
	s_mov_b32 m0, s20
	s_nop 0
	global_load_lds_dwordx4 v[204:205], off
	v_lshl_add_u64 v[204:205], v[216:217], 0, v[204:205]
	v_mfma_f32_32x32x16_bf16 v[96:111], v[136:139], v[148:151], v[96:111]
	s_add_u32 m0, s20, 0x1000
	s_nop 0
	global_load_lds_dwordx4 v[206:207], off
	v_lshl_add_u64 v[206:207], v[216:217], 0, v[206:207]
	v_mfma_f32_32x32x16_bf16 v[80:95], v[140:143], v[148:151], v[80:95]
	s_add_u32 m0, s20, 0x2000
	s_nop 0
	global_load_lds_dwordx4 v[208:209], off
	v_lshl_add_u64 v[208:209], v[216:217], 0, v[208:209]
	v_mfma_f32_32x32x16_bf16 v[64:79], v[144:147], v[148:151], v[64:79]
	s_add_u32 m0, s20, 0x3000
	s_nop 0
	global_load_lds_dwordx4 v[210:211], off
	v_lshl_add_u64 v[210:211], v[216:217], 0, v[210:211]
	v_mfma_f32_32x32x16_bf16 v[48:63], v[128:131], v[132:135], v[48:63]
	s_add_u32 m0, s20, 0x4000
	s_nop 0
	global_load_lds_dwordx4 v[212:213], off
	v_lshl_add_u64 v[212:213], v[216:217], 0, v[212:213]
	v_mfma_f32_32x32x16_bf16 v[32:47], v[136:139], v[132:135], v[32:47]
	s_add_u32 m0, s20, 0x5000
	s_nop 0
	global_load_lds_dwordx4 v[214:215], off
	v_lshl_add_u64 v[214:215], v[216:217], 0, v[214:215]
	v_mfma_f32_32x32x16_bf16 v[16:31], v[140:143], v[132:135], v[16:31]
	v_mfma_f32_32x32x16_bf16 v[0:15], v[144:147], v[132:135], v[0:15]
	ds_read_b128 v[128:131], v159 offset:32768
	ds_read_b128 v[148:151], v158 offset:24576
	ds_read_b128 v[136:139], v159 offset:34816
	ds_read_b128 v[132:135], v158 offset:26624
	ds_read_b128 v[140:143], v159 offset:36864
	ds_read_b128 v[144:147], v159 offset:38912
	s_add_u32 s18, s18, 1
	s_cmp_lg_u32 s18, 9
	s_cbranch_scc1 .Lr0_dma_loop
	s_waitcnt lgkmcnt(10)
	v_mfma_f32_32x32x16_bf16 v[112:127], v[162:165], v[178:181], v[112:127]
	s_waitcnt lgkmcnt(9)
	v_mfma_f32_32x32x16_bf16 v[96:111], v[166:169], v[178:181], v[96:111]
	s_waitcnt lgkmcnt(7)
	v_mfma_f32_32x32x16_bf16 v[80:95], v[170:173], v[178:181], v[80:95]
	s_waitcnt lgkmcnt(6)
	v_mfma_f32_32x32x16_bf16 v[64:79], v[174:177], v[178:181], v[64:79]
	v_mfma_f32_32x32x16_bf16 v[48:63], v[162:165], v[200:203], v[48:63]
	v_mfma_f32_32x32x16_bf16 v[32:47], v[166:169], v[200:203], v[32:47]
	v_mfma_f32_32x32x16_bf16 v[16:31], v[170:173], v[200:203], v[16:31]
	v_mfma_f32_32x32x16_bf16 v[0:15], v[174:177], v[200:203], v[0:15]
	s_waitcnt vmcnt(6)
	s_waitcnt lgkmcnt(0)
	s_barrier
	ds_read_b128 v[162:165], v157 offset:57344
	ds_read_b128 v[178:181], v161 offset:49152
	ds_read_b128 v[166:169], v157 offset:59392
	ds_read_b128 v[200:203], v161 offset:51200
	ds_read_b128 v[170:173], v157 offset:61440
	ds_read_b128 v[174:177], v157 offset:63488
	v_mfma_f32_32x32x16_bf16 v[112:127], v[128:131], v[148:151], v[112:127]
	s_add_u32 m0, s20, 0x6000
	s_nop 0
	global_load_lds_dwordx4 v[204:205], off
	v_lshl_add_u64 v[204:205], v[216:217], 0, v[204:205]
	v_mfma_f32_32x32x16_bf16 v[96:111], v[136:139], v[148:151], v[96:111]
	s_add_u32 m0, s20, 0x7000
	s_nop 0
	global_load_lds_dwordx4 v[206:207], off
	v_lshl_add_u64 v[206:207], v[216:217], 0, v[206:207]
	v_mfma_f32_32x32x16_bf16 v[80:95], v[140:143], v[148:151], v[80:95]
	s_add_u32 m0, s20, 0x8000
	s_nop 0
	global_load_lds_dwordx4 v[208:209], off
	v_lshl_add_u64 v[208:209], v[216:217], 0, v[208:209]
	v_mfma_f32_32x32x16_bf16 v[64:79], v[144:147], v[148:151], v[64:79]
	s_add_u32 m0, s20, 0x9000
	s_nop 0
	global_load_lds_dwordx4 v[210:211], off
	v_lshl_add_u64 v[210:211], v[216:217], 0, v[210:211]
	v_mfma_f32_32x32x16_bf16 v[48:63], v[128:131], v[132:135], v[48:63]
	s_add_u32 m0, s20, 0xa000
	s_nop 0
	global_load_lds_dwordx4 v[212:213], off
	v_lshl_add_u64 v[212:213], v[216:217], 0, v[212:213]
	v_mfma_f32_32x32x16_bf16 v[32:47], v[136:139], v[132:135], v[32:47]
	s_add_u32 m0, s20, 0xb000
	s_nop 0
	global_load_lds_dwordx4 v[214:215], off
	v_lshl_add_u64 v[214:215], v[216:217], 0, v[214:215]
	v_mfma_f32_32x32x16_bf16 v[16:31], v[140:143], v[132:135], v[16:31]
	v_mfma_f32_32x32x16_bf16 v[0:15], v[144:147], v[132:135], v[0:15]
	ds_read_b128 v[128:131], v159 offset:57344
	ds_read_b128 v[148:151], v158 offset:49152
	ds_read_b128 v[136:139], v159 offset:59392
	ds_read_b128 v[132:135], v158 offset:51200
	ds_read_b128 v[140:143], v159 offset:61440
	ds_read_b128 v[144:147], v159 offset:63488
	s_waitcnt lgkmcnt(10)
	v_mfma_f32_32x32x16_bf16 v[112:127], v[162:165], v[178:181], v[112:127]
	s_waitcnt lgkmcnt(9)
	v_mfma_f32_32x32x16_bf16 v[96:111], v[166:169], v[178:181], v[96:111]
	s_waitcnt lgkmcnt(7)
	v_mfma_f32_32x32x16_bf16 v[80:95], v[170:173], v[178:181], v[80:95]
	s_waitcnt lgkmcnt(6)
	v_mfma_f32_32x32x16_bf16 v[64:79], v[174:177], v[178:181], v[64:79]
	v_mfma_f32_32x32x16_bf16 v[48:63], v[162:165], v[200:203], v[48:63]
	v_mfma_f32_32x32x16_bf16 v[32:47], v[166:169], v[200:203], v[32:47]
	v_mfma_f32_32x32x16_bf16 v[16:31], v[170:173], v[200:203], v[16:31]
	v_mfma_f32_32x32x16_bf16 v[0:15], v[174:177], v[200:203], v[0:15]
	s_waitcnt vmcnt(6)
	s_waitcnt lgkmcnt(0)
	s_barrier
	ds_read_b128 v[162:165], v157 offset:8192
	ds_read_b128 v[178:181], v161
	ds_read_b128 v[166:169], v157 offset:10240
	ds_read_b128 v[200:203], v161 offset:2048
	ds_read_b128 v[170:173], v157 offset:12288
	ds_read_b128 v[174:177], v157 offset:14336
	v_mfma_f32_32x32x16_bf16 v[112:127], v[128:131], v[148:151], v[112:127]
	v_mfma_f32_32x32x16_bf16 v[96:111], v[136:139], v[148:151], v[96:111]
	v_mfma_f32_32x32x16_bf16 v[80:95], v[140:143], v[148:151], v[80:95]
	v_mfma_f32_32x32x16_bf16 v[64:79], v[144:147], v[148:151], v[64:79]
	v_mfma_f32_32x32x16_bf16 v[48:63], v[128:131], v[132:135], v[48:63]
	v_mfma_f32_32x32x16_bf16 v[32:47], v[136:139], v[132:135], v[32:47]
	v_mfma_f32_32x32x16_bf16 v[16:31], v[140:143], v[132:135], v[16:31]
	v_mfma_f32_32x32x16_bf16 v[0:15], v[144:147], v[132:135], v[0:15]
	ds_read_b128 v[128:131], v159 offset:8192
	ds_read_b128 v[148:151], v158
	ds_read_b128 v[136:139], v159 offset:10240
	ds_read_b128 v[132:135], v158 offset:2048
	ds_read_b128 v[140:143], v159 offset:12288
	ds_read_b128 v[144:147], v159 offset:14336
	s_waitcnt lgkmcnt(10)
	v_mfma_f32_32x32x16_bf16 v[112:127], v[162:165], v[178:181], v[112:127]
	s_waitcnt lgkmcnt(9)
	v_mfma_f32_32x32x16_bf16 v[96:111], v[166:169], v[178:181], v[96:111]
	s_waitcnt lgkmcnt(7)
	v_mfma_f32_32x32x16_bf16 v[80:95], v[170:173], v[178:181], v[80:95]
	s_waitcnt lgkmcnt(6)
	v_mfma_f32_32x32x16_bf16 v[64:79], v[174:177], v[178:181], v[64:79]
	v_mfma_f32_32x32x16_bf16 v[48:63], v[162:165], v[200:203], v[48:63]
	v_mfma_f32_32x32x16_bf16 v[32:47], v[166:169], v[200:203], v[32:47]
	v_mfma_f32_32x32x16_bf16 v[16:31], v[170:173], v[200:203], v[16:31]
	v_mfma_f32_32x32x16_bf16 v[0:15], v[174:177], v[200:203], v[0:15]
	s_waitcnt vmcnt(0)
	s_waitcnt lgkmcnt(0)
	s_barrier
	ds_read_b128 v[162:165], v157 offset:32768
	ds_read_b128 v[178:181], v161 offset:24576
	ds_read_b128 v[166:169], v157 offset:34816
	ds_read_b128 v[200:203], v161 offset:26624
	ds_read_b128 v[170:173], v157 offset:36864
	ds_read_b128 v[174:177], v157 offset:38912
	v_mfma_f32_32x32x16_bf16 v[112:127], v[128:131], v[148:151], v[112:127]
	v_mfma_f32_32x32x16_bf16 v[96:111], v[136:139], v[148:151], v[96:111]
	v_mfma_f32_32x32x16_bf16 v[80:95], v[140:143], v[148:151], v[80:95]
	v_mfma_f32_32x32x16_bf16 v[64:79], v[144:147], v[148:151], v[64:79]
	v_mfma_f32_32x32x16_bf16 v[48:63], v[128:131], v[132:135], v[48:63]
	v_mfma_f32_32x32x16_bf16 v[32:47], v[136:139], v[132:135], v[32:47]
	v_mfma_f32_32x32x16_bf16 v[16:31], v[140:143], v[132:135], v[16:31]
	v_mfma_f32_32x32x16_bf16 v[0:15], v[144:147], v[132:135], v[0:15]
	ds_read_b128 v[128:131], v159 offset:32768
	ds_read_b128 v[148:151], v158 offset:24576
	ds_read_b128 v[136:139], v159 offset:34816
	ds_read_b128 v[132:135], v158 offset:26624
	ds_read_b128 v[140:143], v159 offset:36864
	ds_read_b128 v[144:147], v159 offset:38912
	s_waitcnt lgkmcnt(10)
	v_mfma_f32_32x32x16_bf16 v[112:127], v[162:165], v[178:181], v[112:127]
	s_waitcnt lgkmcnt(9)
	v_mfma_f32_32x32x16_bf16 v[96:111], v[166:169], v[178:181], v[96:111]
	s_waitcnt lgkmcnt(7)
	v_mfma_f32_32x32x16_bf16 v[80:95], v[170:173], v[178:181], v[80:95]
	s_waitcnt lgkmcnt(6)
	v_mfma_f32_32x32x16_bf16 v[64:79], v[174:177], v[178:181], v[64:79]
	v_mfma_f32_32x32x16_bf16 v[48:63], v[162:165], v[200:203], v[48:63]
	v_mfma_f32_32x32x16_bf16 v[32:47], v[166:169], v[200:203], v[32:47]
	v_mfma_f32_32x32x16_bf16 v[16:31], v[170:173], v[200:203], v[16:31]
	v_mfma_f32_32x32x16_bf16 v[0:15], v[174:177], v[200:203], v[0:15]
	s_waitcnt lgkmcnt(4)
	v_mfma_f32_32x32x16_bf16 v[112:127], v[128:131], v[148:151], v[112:127]
	s_waitcnt lgkmcnt(3)
	v_mfma_f32_32x32x16_bf16 v[96:111], v[136:139], v[148:151], v[96:111]
	s_waitcnt lgkmcnt(1)
	v_mfma_f32_32x32x16_bf16 v[80:95], v[140:143], v[148:151], v[80:95]
	s_waitcnt lgkmcnt(0)
	v_mfma_f32_32x32x16_bf16 v[64:79], v[144:147], v[148:151], v[64:79]
	s_mov_b32 s20, 0x1344000
	s_waitcnt lgkmcnt(0)
	s_barrier
	v_mfma_f32_32x32x16_bf16 v[48:63], v[128:131], v[132:135], v[48:63]
	v_ashrrev_i32_e32 v128, 1, v156
	v_and_b32_e32 v128, 0xffffffc0, v128
	v_add_u32_e32 v128, s46, v128
	v_mfma_f32_32x32x16_bf16 v[32:47], v[136:139], v[132:135], v[32:47]
	v_and_or_b32 v136, v156, 31, v128
	v_cmp_lt_i32_e32 vcc, s57, v136
	v_mfma_f32_32x32x16_bf16 v[16:31], v[140:143], v[132:135], v[16:31]
	v_mfma_f32_32x32x16_bf16 v[0:15], v[144:147], v[132:135], v[0:15]
	s_and_saveexec_b64 s[18:19], vcc
	s_xor_b64 s[18:19], exec, s[18:19]
	v_add_u32_e32 v190, 0xffffc000, v136
	v_mov_b64_e32 v[128:129], v[190:191]
	s_or_saveexec_b64 s[18:19], s[18:19]
	v_mov_b32_e32 v134, 0
	v_mov_b64_e32 v[132:133], 0
	v_mov_b64_e32 v[130:131], s[14:15]
	s_xor_b64 exec, exec, s[18:19]
	v_add_u32_e32 v128, s44, v136
	v_ashrrev_i32_e32 v129, 12, v128
	v_add_u32_e32 v134, 1, v129
	v_ashrrev_i32_e32 v129, 31, v128
	v_mov_b64_e32 v[132:133], 0x400000
	v_mov_b64_e32 v[130:131], s[4:5]
	s_or_b64 exec, exec, s[18:19]
	v_lshlrev_b32_e32 v133, 1, v156
	v_lshrrev_b32_e32 v135, 3, v156
	s_lshl_b32 s18, s45, 8
	v_and_b32_e32 v133, 0x80, v133
	v_and_b32_e32 v135, 4, v135
	v_or3_b32 v138, v135, v133, s18
	v_readlane_b32 s18, v252, 0
	v_readlane_b32 s19, v252, 1
	v_readlane_b32 s60, v252, 4
	v_add_u32_e32 v133, s2, v134
	v_mov_b64_e32 v[134:135], s[18:19]
	v_lshlrev_b32_e32 v190, 2, v132
	v_readlane_b32 s72, v252, 16
	v_readlane_b32 s73, v252, 17
	v_mad_i64_i32 v[140:141], s[18:19], v133, s88, v[134:135]
	s_nop 0
	v_lshl_add_u64 v[132:133], s[72:73], 0, v[190:191]
	v_lshlrev_b64 v[128:129], 12, v[128:129]
	v_cndmask_b32_e64 v131, v133, v131, s[40:41]
	v_cndmask_b32_e64 v130, v132, v130, s[40:41]
	v_ashrrev_i32_e32 v139, 31, v138
	v_lshl_add_u64 v[142:143], v[132:133], 0, v[128:129]
	v_lshl_add_u64 v[130:131], v[130:131], 0, v[128:129]
	v_lshlrev_b64 v[128:129], 2, v[138:139]
	v_lshl_add_u64 v[134:135], v[130:131], 0, v[128:129]
	v_lshl_add_u64 v[132:133], v[140:141], 0, v[128:129]
	v_lshl_add_u64 v[130:131], v[142:143], 0, v[128:129]
	flat_load_dwordx4 v[138:141], v[134:135]
	global_load_dwordx4 v[142:145], v[132:133], off
	v_readlane_b32 s61, v252, 5
	v_readlane_b32 s62, v252, 6
	v_readlane_b32 s63, v252, 7
	v_readlane_b32 s64, v252, 8
	v_readlane_b32 s65, v252, 9
	v_readlane_b32 s66, v252, 10
	v_readlane_b32 s67, v252, 11
	v_readlane_b32 s68, v252, 12
	v_readlane_b32 s69, v252, 13
	v_readlane_b32 s70, v252, 14
	v_readlane_b32 s71, v252, 15
	v_readlane_b32 s74, v252, 18
	v_readlane_b32 s75, v252, 19
	s_waitcnt vmcnt(0) lgkmcnt(0)
	v_pk_fma_f32 v[112:113], v[112:113], v[142:143], v[138:139]
	v_pk_fma_f32 v[114:115], v[114:115], v[144:145], v[140:141]
	global_store_dwordx4 v[130:131], v[112:115], off
	flat_load_dwordx4 v[112:115], v[134:135] offset:32
	s_nop 0
	global_load_dwordx4 v[138:141], v[132:133], off offset:32
	s_waitcnt vmcnt(0) lgkmcnt(0)
	v_pk_fma_f32 v[112:113], v[116:117], v[138:139], v[112:113]
	v_pk_fma_f32 v[114:115], v[118:119], v[140:141], v[114:115]
	global_store_dwordx4 v[130:131], v[112:115], off offset:32
	flat_load_dwordx4 v[112:115], v[134:135] offset:64
	s_nop 0
	global_load_dwordx4 v[116:119], v[132:133], off offset:64
	s_waitcnt vmcnt(0) lgkmcnt(0)
	v_pk_fma_f32 v[112:113], v[120:121], v[116:117], v[112:113]
	v_pk_fma_f32 v[114:115], v[122:123], v[118:119], v[114:115]
	global_store_dwordx4 v[130:131], v[112:115], off offset:64
	flat_load_dwordx4 v[112:115], v[134:135] offset:96
	s_nop 0
	global_load_dwordx4 v[116:119], v[132:133], off offset:96
	s_waitcnt vmcnt(0) lgkmcnt(0)
	v_pk_fma_f32 v[112:113], v[124:125], v[116:117], v[112:113]
	v_pk_fma_f32 v[114:115], v[126:127], v[118:119], v[114:115]
	global_store_dwordx4 v[130:131], v[112:115], off offset:96
	flat_load_dwordx4 v[112:115], v[134:135] offset:128
	s_nop 0
	global_load_dwordx4 v[116:119], v[132:133], off offset:128
	s_waitcnt vmcnt(0) lgkmcnt(0)
	v_pk_fma_f32 v[96:97], v[96:97], v[116:117], v[112:113]
	v_pk_fma_f32 v[98:99], v[98:99], v[118:119], v[114:115]
	global_store_dwordx4 v[130:131], v[96:99], off offset:128
	flat_load_dwordx4 v[96:99], v[134:135] offset:160
	s_nop 0
	global_load_dwordx4 v[112:115], v[132:133], off offset:160
	s_waitcnt vmcnt(0) lgkmcnt(0)
	v_pk_fma_f32 v[96:97], v[100:101], v[112:113], v[96:97]
	v_pk_fma_f32 v[98:99], v[102:103], v[114:115], v[98:99]
	global_store_dwordx4 v[130:131], v[96:99], off offset:160
	flat_load_dwordx4 v[96:99], v[134:135] offset:192
	s_nop 0
	global_load_dwordx4 v[100:103], v[132:133], off offset:192
	s_waitcnt vmcnt(0) lgkmcnt(0)
	v_pk_fma_f32 v[96:97], v[104:105], v[100:101], v[96:97]
	v_pk_fma_f32 v[98:99], v[106:107], v[102:103], v[98:99]
	global_store_dwordx4 v[130:131], v[96:99], off offset:192
	flat_load_dwordx4 v[96:99], v[134:135] offset:224
	s_nop 0
	global_load_dwordx4 v[100:103], v[132:133], off offset:224
	s_waitcnt vmcnt(0) lgkmcnt(0)
	v_pk_fma_f32 v[96:97], v[108:109], v[100:101], v[96:97]
	v_pk_fma_f32 v[98:99], v[110:111], v[102:103], v[98:99]
	global_store_dwordx4 v[130:131], v[96:99], off offset:224
	flat_load_dwordx4 v[96:99], v[134:135] offset:256
	s_nop 0
	global_load_dwordx4 v[100:103], v[132:133], off offset:256
	s_waitcnt vmcnt(0) lgkmcnt(0)
	v_pk_fma_f32 v[80:81], v[80:81], v[100:101], v[96:97]
	v_pk_fma_f32 v[82:83], v[82:83], v[102:103], v[98:99]
	global_store_dwordx4 v[130:131], v[80:83], off offset:256
	flat_load_dwordx4 v[80:83], v[134:135] offset:288
	s_nop 0
	global_load_dwordx4 v[96:99], v[132:133], off offset:288
	s_waitcnt vmcnt(0) lgkmcnt(0)
	v_pk_fma_f32 v[80:81], v[84:85], v[96:97], v[80:81]
	v_pk_fma_f32 v[82:83], v[86:87], v[98:99], v[82:83]
	global_store_dwordx4 v[130:131], v[80:83], off offset:288
	flat_load_dwordx4 v[80:83], v[134:135] offset:320
	s_nop 0
	global_load_dwordx4 v[84:87], v[132:133], off offset:320
	s_waitcnt vmcnt(0) lgkmcnt(0)
	v_pk_fma_f32 v[80:81], v[88:89], v[84:85], v[80:81]
	v_pk_fma_f32 v[82:83], v[90:91], v[86:87], v[82:83]
	global_store_dwordx4 v[130:131], v[80:83], off offset:320
	flat_load_dwordx4 v[80:83], v[134:135] offset:352
	s_nop 0
	global_load_dwordx4 v[84:87], v[132:133], off offset:352
	s_waitcnt vmcnt(0) lgkmcnt(0)
	v_pk_fma_f32 v[80:81], v[92:93], v[84:85], v[80:81]
	v_pk_fma_f32 v[82:83], v[94:95], v[86:87], v[82:83]
	global_store_dwordx4 v[130:131], v[80:83], off offset:352
	flat_load_dwordx4 v[80:83], v[134:135] offset:384
	s_nop 0
	global_load_dwordx4 v[84:87], v[132:133], off offset:384
	s_waitcnt vmcnt(0) lgkmcnt(0)
	v_pk_fma_f32 v[64:65], v[64:65], v[84:85], v[80:81]
	v_pk_fma_f32 v[66:67], v[66:67], v[86:87], v[82:83]
	global_store_dwordx4 v[130:131], v[64:67], off offset:384
	flat_load_dwordx4 v[64:67], v[134:135] offset:416
	s_nop 0
	global_load_dwordx4 v[80:83], v[132:133], off offset:416
	s_waitcnt vmcnt(0) lgkmcnt(0)
	v_pk_fma_f32 v[64:65], v[68:69], v[80:81], v[64:65]
	v_pk_fma_f32 v[66:67], v[70:71], v[82:83], v[66:67]
	global_store_dwordx4 v[130:131], v[64:67], off offset:416
	flat_load_dwordx4 v[64:67], v[134:135] offset:448
	s_nop 0
	global_load_dwordx4 v[68:71], v[132:133], off offset:448
	s_waitcnt vmcnt(0) lgkmcnt(0)
	v_pk_fma_f32 v[64:65], v[72:73], v[68:69], v[64:65]
	v_pk_fma_f32 v[66:67], v[74:75], v[70:71], v[66:67]
	global_store_dwordx4 v[130:131], v[64:67], off offset:448
	flat_load_dwordx4 v[64:67], v[134:135] offset:480
	s_nop 0
	global_load_dwordx4 v[68:71], v[132:133], off offset:480
	s_waitcnt vmcnt(0) lgkmcnt(0)
	v_pk_fma_f32 v[66:67], v[78:79], v[70:71], v[66:67]
	v_or_b32_e32 v70, 32, v136
	v_pk_fma_f32 v[64:65], v[76:77], v[68:69], v[64:65]
	v_cmp_lt_i32_e32 vcc, s57, v70
	global_store_dwordx4 v[130:131], v[64:67], off offset:480
	s_and_saveexec_b64 s[18:19], vcc
	s_xor_b64 s[18:19], exec, s[18:19]
	v_add_u32_e32 v190, 0xffffc020, v136
	v_mov_b64_e32 v[64:65], v[190:191]
	s_or_saveexec_b64 s[18:19], s[18:19]
	v_mov_b32_e32 v71, 0
	v_mov_b64_e32 v[68:69], 0
	v_mov_b64_e32 v[66:67], s[14:15]
	s_xor_b64 exec, exec, s[18:19]
	s_cbranch_execz .LBB0_920
	v_add_u32_e32 v64, s44, v70
	v_ashrrev_i32_e32 v65, 12, v64
	v_add_u32_e32 v71, 1, v65
	v_ashrrev_i32_e32 v65, 31, v64
	v_mov_b64_e32 v[68:69], 0x400000
	v_mov_b64_e32 v[66:67], s[4:5]
	s_branch .LBB0_920

.LBB0_1066:
	v_add_co_u32_e32 v182, vcc, 0x800, v152
	s_nop 1
	v_addc_co_u32_e32 v183, vcc, 0, v153, vcc
	v_add_co_u32_e32 v204, vcc, s34, v182
	s_nop 1
	v_addc_co_u32_e32 v205, vcc, 0, v183, vcc
	v_add_co_u32_e32 v206, vcc, s35, v182
	s_nop 1
	v_addc_co_u32_e32 v207, vcc, 0, v183, vcc
	v_add_co_u32_e32 v208, vcc, 0x14fe000, v154
	s_nop 1
	v_addc_co_u32_e32 v209, vcc, 0, v155, vcc
	v_add_co_u32_e32 v210, vcc, 0x1520000, v154
	s_nop 1
	v_addc_co_u32_e32 v211, vcc, 0, v155, vcc
	v_add_co_u32_e32 v212, vcc, 0x1542000, v154
	s_nop 1
	v_addc_co_u32_e32 v213, vcc, 0, v155, vcc
	v_add_co_u32_e32 v214, vcc, 0x1564000, v154
	s_nop 1
	v_addc_co_u32_e32 v215, vcc, 0, v155, vcc
	v_and_b32_e32 v216, 3, v156
	v_bfe_u32 v217, v156, 4, 2
	v_xor_b32_e32 v218, v216, v217
	v_sub_u32_e32 v218, v218, v216
	v_lshlrev_b32_e32 v218, 4, v218
	v_ashrrev_i32_e32 v219, 31, v218
	v_lshl_add_u64 v[204:205], v[218:219], 0, v[204:205]
	v_lshl_add_u64 v[206:207], v[218:219], 0, v[206:207]
	v_lshl_add_u64 v[208:209], v[218:219], 0, v[208:209]
	v_lshl_add_u64 v[210:211], v[218:219], 0, v[210:211]
	v_lshl_add_u64 v[212:213], v[218:219], 0, v[212:213]
	v_lshl_add_u64 v[214:215], v[218:219], 0, v[214:215]
	v_mov_b32_e32 v216, 64
	v_mov_b32_e32 v217, 0
	v_lshl_add_u64 v[204:205], v[216:217], 1, v[204:205]
	v_lshl_add_u64 v[206:207], v[216:217], 1, v[206:207]
	v_lshl_add_u64 v[208:209], v[216:217], 1, v[208:209]
	v_lshl_add_u64 v[210:211], v[216:217], 1, v[210:211]
	v_lshl_add_u64 v[212:213], v[216:217], 1, v[212:213]
	v_lshl_add_u64 v[214:215], v[216:217], 1, v[214:215]
	v_lshrrev_b32_e32 v246, 6, v156
	v_lshlrev_b32_e32 v246, 10, v246
	s_nop 0
	v_readfirstlane_b32 s14, v246
	ds_read_b128 v[162:165], v159 offset:8192
	ds_read_b128 v[178:181], v158
	ds_read_b128 v[166:169], v159 offset:10240
	ds_read_b128 v[200:203], v158 offset:2048
	ds_read_b128 v[170:173], v159 offset:12288
	ds_read_b128 v[174:177], v159 offset:14336
	s_waitcnt lgkmcnt(4)
	v_mfma_f32_32x32x16_bf16 v[112:127], v[162:165], v[178:181], v[112:127]
	s_waitcnt lgkmcnt(3)
	v_mfma_f32_32x32x16_bf16 v[96:111], v[166:169], v[178:181], v[96:111]
	s_waitcnt lgkmcnt(1)
	v_mfma_f32_32x32x16_bf16 v[80:95], v[170:173], v[178:181], v[80:95]
	s_waitcnt lgkmcnt(0)
	v_mfma_f32_32x32x16_bf16 v[64:79], v[174:177], v[178:181], v[64:79]
	v_mfma_f32_32x32x16_bf16 v[48:63], v[162:165], v[200:203], v[48:63]
	v_mfma_f32_32x32x16_bf16 v[32:47], v[166:169], v[200:203], v[32:47]
	v_mfma_f32_32x32x16_bf16 v[16:31], v[170:173], v[200:203], v[16:31]
	v_mfma_f32_32x32x16_bf16 v[0:15], v[174:177], v[200:203], v[0:15]
	ds_read_b128 v[162:165], v157 offset:8192
	ds_read_b128 v[178:181], v160
	ds_read_b128 v[166:169], v157 offset:10240
	ds_read_b128 v[200:203], v160 offset:2048
	ds_read_b128 v[170:173], v157 offset:12288
	ds_read_b128 v[174:177], v157 offset:14336
	s_waitcnt vmcnt(5)
	ds_write_b128 v161, v[144:147] offset:24576
	s_waitcnt vmcnt(3)
	ds_write_b128 v161, v[148:151] offset:28672
	ds_write_b128 v161, v[140:143] offset:32768
	s_waitcnt vmcnt(2)
	ds_write_b128 v161, v[132:135] offset:36864
	s_waitcnt vmcnt(1)
	ds_write_b128 v161, v[128:131] offset:40960
	s_waitcnt vmcnt(0)
	ds_write_b128 v161, v[136:139] offset:45056
	s_add_u32 m0, s14, 0xc000
	s_nop 0
	global_load_lds_dwordx4 v[204:205], off
	v_lshl_add_u64 v[204:205], v[216:217], 0, v[204:205]
	s_add_u32 m0, s14, 0xd000
	s_nop 0
	global_load_lds_dwordx4 v[206:207], off
	v_lshl_add_u64 v[206:207], v[216:217], 0, v[206:207]
	s_add_u32 m0, s14, 0xe000
	s_nop 0
	global_load_lds_dwordx4 v[208:209], off
	v_lshl_add_u64 v[208:209], v[216:217], 0, v[208:209]
	s_add_u32 m0, s14, 0xf000
	s_nop 0
	global_load_lds_dwordx4 v[210:211], off
	v_lshl_add_u64 v[210:211], v[216:217], 0, v[210:211]
	s_add_u32 m0, s14, 0x10000
	s_nop 0
	global_load_lds_dwordx4 v[212:213], off
	v_lshl_add_u64 v[212:213], v[216:217], 0, v[212:213]
	s_add_u32 m0, s14, 0x11000
	s_nop 0
	global_load_lds_dwordx4 v[214:215], off
	v_lshl_add_u64 v[214:215], v[216:217], 0, v[214:215]
	s_waitcnt lgkmcnt(10)
	v_mfma_f32_32x32x16_bf16 v[112:127], v[162:165], v[178:181], v[112:127]
	s_waitcnt lgkmcnt(9)
	v_mfma_f32_32x32x16_bf16 v[96:111], v[166:169], v[178:181], v[96:111]
	s_waitcnt lgkmcnt(7)
	v_mfma_f32_32x32x16_bf16 v[80:95], v[170:173], v[178:181], v[80:95]
	s_waitcnt lgkmcnt(6)
	v_mfma_f32_32x32x16_bf16 v[64:79], v[174:177], v[178:181], v[64:79]
	v_mfma_f32_32x32x16_bf16 v[48:63], v[162:165], v[200:203], v[48:63]
	v_mfma_f32_32x32x16_bf16 v[32:47], v[166:169], v[200:203], v[32:47]
	v_mfma_f32_32x32x16_bf16 v[16:31], v[170:173], v[200:203], v[16:31]
	v_mfma_f32_32x32x16_bf16 v[0:15], v[174:177], v[200:203], v[0:15]
	s_waitcnt lgkmcnt(0)
	s_barrier
	ds_read_b128 v[162:165], v159 offset:32768
	ds_read_b128 v[178:181], v158 offset:24576
	ds_read_b128 v[166:169], v159 offset:34816
	ds_read_b128 v[200:203], v158 offset:26624
	ds_read_b128 v[170:173], v159 offset:36864
	ds_read_b128 v[174:177], v159 offset:38912
	ds_read_b128 v[128:131], v157 offset:32768
	ds_read_b128 v[144:147], v160 offset:24576
	ds_read_b128 v[132:135], v157 offset:34816
	ds_read_b128 v[148:151], v160 offset:26624
	ds_read_b128 v[136:139], v157 offset:36864
	ds_read_b128 v[140:143], v157 offset:38912
	s_mov_b32 m0, s14
	s_nop 0
	global_load_lds_dwordx4 v[204:205], off
	v_lshl_add_u64 v[204:205], v[216:217], 0, v[204:205]
	s_add_u32 m0, s14, 0x1000
	s_nop 0
	global_load_lds_dwordx4 v[206:207], off
	v_lshl_add_u64 v[206:207], v[216:217], 0, v[206:207]
	s_add_u32 m0, s14, 0x2000
	s_nop 0
	global_load_lds_dwordx4 v[208:209], off
	v_lshl_add_u64 v[208:209], v[216:217], 0, v[208:209]
	s_add_u32 m0, s14, 0x3000
	s_nop 0
	global_load_lds_dwordx4 v[210:211], off
	v_lshl_add_u64 v[210:211], v[216:217], 0, v[210:211]
	s_add_u32 m0, s14, 0x4000
	s_nop 0
	global_load_lds_dwordx4 v[212:213], off
	v_lshl_add_u64 v[212:213], v[216:217], 0, v[212:213]
	s_add_u32 m0, s14, 0x5000
	s_nop 0
	global_load_lds_dwordx4 v[214:215], off
	v_lshl_add_u64 v[214:215], v[216:217], 0, v[214:215]
	s_mov_b32 s15, 0
.Lup_dma_loop:
	s_waitcnt lgkmcnt(10)
	v_mfma_f32_32x32x16_bf16 v[112:127], v[162:165], v[178:181], v[112:127]
	s_waitcnt lgkmcnt(9)
	v_mfma_f32_32x32x16_bf16 v[96:111], v[166:169], v[178:181], v[96:111]
	s_waitcnt lgkmcnt(7)
	v_mfma_f32_32x32x16_bf16 v[80:95], v[170:173], v[178:181], v[80:95]
	s_waitcnt lgkmcnt(6)
	v_mfma_f32_32x32x16_bf16 v[64:79], v[174:177], v[178:181], v[64:79]
	v_mfma_f32_32x32x16_bf16 v[48:63], v[162:165], v[200:203], v[48:63]
	v_mfma_f32_32x32x16_bf16 v[32:47], v[166:169], v[200:203], v[32:47]
	v_mfma_f32_32x32x16_bf16 v[16:31], v[170:173], v[200:203], v[16:31]
	v_mfma_f32_32x32x16_bf16 v[0:15], v[174:177], v[200:203], v[0:15]
	s_waitcnt vmcnt(6)
	s_waitcnt lgkmcnt(0)
	s_barrier
	ds_read_b128 v[162:165], v159 offset:57344
	ds_read_b128 v[178:181], v158 offset:49152
	ds_read_b128 v[166:169], v159 offset:59392
	ds_read_b128 v[200:203], v158 offset:51200
	ds_read_b128 v[170:173], v159 offset:61440
	ds_read_b128 v[174:177], v159 offset:63488
	v_mfma_f32_32x32x16_bf16 v[112:127], v[128:131], v[144:147], v[112:127]
	s_add_u32 m0, s14, 0x6000
	s_nop 0
	global_load_lds_dwordx4 v[204:205], off
	v_lshl_add_u64 v[204:205], v[216:217], 0, v[204:205]
	v_mfma_f32_32x32x16_bf16 v[96:111], v[132:135], v[144:147], v[96:111]
	s_add_u32 m0, s14, 0x7000
	s_nop 0
	global_load_lds_dwordx4 v[206:207], off
	v_lshl_add_u64 v[206:207], v[216:217], 0, v[206:207]
	v_mfma_f32_32x32x16_bf16 v[80:95], v[136:139], v[144:147], v[80:95]
	s_add_u32 m0, s14, 0x8000
	s_nop 0
	global_load_lds_dwordx4 v[208:209], off
	v_lshl_add_u64 v[208:209], v[216:217], 0, v[208:209]
	v_mfma_f32_32x32x16_bf16 v[64:79], v[140:143], v[144:147], v[64:79]
	s_add_u32 m0, s14, 0x9000
	s_nop 0
	global_load_lds_dwordx4 v[210:211], off
	v_lshl_add_u64 v[210:211], v[216:217], 0, v[210:211]
	v_mfma_f32_32x32x16_bf16 v[48:63], v[128:131], v[148:151], v[48:63]
	s_add_u32 m0, s14, 0xa000
	s_nop 0
	global_load_lds_dwordx4 v[212:213], off
	v_lshl_add_u64 v[212:213], v[216:217], 0, v[212:213]
	v_mfma_f32_32x32x16_bf16 v[32:47], v[132:135], v[148:151], v[32:47]
	s_add_u32 m0, s14, 0xb000
	s_nop 0
	global_load_lds_dwordx4 v[214:215], off
	v_lshl_add_u64 v[214:215], v[216:217], 0, v[214:215]
	v_mfma_f32_32x32x16_bf16 v[16:31], v[136:139], v[148:151], v[16:31]
	v_mfma_f32_32x32x16_bf16 v[0:15], v[140:143], v[148:151], v[0:15]
	ds_read_b128 v[128:131], v157 offset:57344
	ds_read_b128 v[144:147], v160 offset:49152
	ds_read_b128 v[132:135], v157 offset:59392
	ds_read_b128 v[148:151], v160 offset:51200
	ds_read_b128 v[136:139], v157 offset:61440
	ds_read_b128 v[140:143], v157 offset:63488
	s_waitcnt lgkmcnt(10)
	v_mfma_f32_32x32x16_bf16 v[112:127], v[162:165], v[178:181], v[112:127]
	s_waitcnt lgkmcnt(9)
	v_mfma_f32_32x32x16_bf16 v[96:111], v[166:169], v[178:181], v[96:111]
	s_waitcnt lgkmcnt(7)
	v_mfma_f32_32x32x16_bf16 v[80:95], v[170:173], v[178:181], v[80:95]
	s_waitcnt lgkmcnt(6)
	v_mfma_f32_32x32x16_bf16 v[64:79], v[174:177], v[178:181], v[64:79]
	v_mfma_f32_32x32x16_bf16 v[48:63], v[162:165], v[200:203], v[48:63]
	v_mfma_f32_32x32x16_bf16 v[32:47], v[166:169], v[200:203], v[32:47]
	v_mfma_f32_32x32x16_bf16 v[16:31], v[170:173], v[200:203], v[16:31]
	v_mfma_f32_32x32x16_bf16 v[0:15], v[174:177], v[200:203], v[0:15]
	s_waitcnt vmcnt(6)
	s_waitcnt lgkmcnt(0)
	s_barrier
	ds_read_b128 v[162:165], v159 offset:8192
	ds_read_b128 v[178:181], v158
	ds_read_b128 v[166:169], v159 offset:10240
	ds_read_b128 v[200:203], v158 offset:2048
	ds_read_b128 v[170:173], v159 offset:12288
	ds_read_b128 v[174:177], v159 offset:14336
	v_mfma_f32_32x32x16_bf16 v[112:127], v[128:131], v[144:147], v[112:127]
	s_add_u32 m0, s14, 0xc000
	s_nop 0
	global_load_lds_dwordx4 v[204:205], off
	v_lshl_add_u64 v[204:205], v[216:217], 0, v[204:205]
	v_mfma_f32_32x32x16_bf16 v[96:111], v[132:135], v[144:147], v[96:111]
	s_add_u32 m0, s14, 0xd000
	s_nop 0
	global_load_lds_dwordx4 v[206:207], off
	v_lshl_add_u64 v[206:207], v[216:217], 0, v[206:207]
	v_mfma_f32_32x32x16_bf16 v[80:95], v[136:139], v[144:147], v[80:95]
	s_add_u32 m0, s14, 0xe000
	s_nop 0
	global_load_lds_dwordx4 v[208:209], off
	v_lshl_add_u64 v[208:209], v[216:217], 0, v[208:209]
	v_mfma_f32_32x32x16_bf16 v[64:79], v[140:143], v[144:147], v[64:79]
	s_add_u32 m0, s14, 0xf000
	s_nop 0
	global_load_lds_dwordx4 v[210:211], off
	v_lshl_add_u64 v[210:211], v[216:217], 0, v[210:211]
	v_mfma_f32_32x32x16_bf16 v[48:63], v[128:131], v[148:151], v[48:63]
	s_add_u32 m0, s14, 0x10000
	s_nop 0
	global_load_lds_dwordx4 v[212:213], off
	v_lshl_add_u64 v[212:213], v[216:217], 0, v[212:213]
	v_mfma_f32_32x32x16_bf16 v[32:47], v[132:135], v[148:151], v[32:47]
	s_add_u32 m0, s14, 0x11000
	s_nop 0
	global_load_lds_dwordx4 v[214:215], off
	v_lshl_add_u64 v[214:215], v[216:217], 0, v[214:215]
	v_mfma_f32_32x32x16_bf16 v[16:31], v[136:139], v[148:151], v[16:31]
	v_mfma_f32_32x32x16_bf16 v[0:15], v[140:143], v[148:151], v[0:15]
	ds_read_b128 v[128:131], v157 offset:8192
	ds_read_b128 v[144:147], v160
	ds_read_b128 v[132:135], v157 offset:10240
	ds_read_b128 v[148:151], v160 offset:2048
	ds_read_b128 v[136:139], v157 offset:12288
	ds_read_b128 v[140:143], v157 offset:14336
	s_waitcnt lgkmcnt(10)
	v_mfma_f32_32x32x16_bf16 v[112:127], v[162:165], v[178:181], v[112:127]
	s_waitcnt lgkmcnt(9)
	v_mfma_f32_32x32x16_bf16 v[96:111], v[166:169], v[178:181], v[96:111]
	s_waitcnt lgkmcnt(7)
	v_mfma_f32_32x32x16_bf16 v[80:95], v[170:173], v[178:181], v[80:95]
	s_waitcnt lgkmcnt(6)
	v_mfma_f32_32x32x16_bf16 v[64:79], v[174:177], v[178:181], v[64:79]
	v_mfma_f32_32x32x16_bf16 v[48:63], v[162:165], v[200:203], v[48:63]
	v_mfma_f32_32x32x16_bf16 v[32:47], v[166:169], v[200:203], v[32:47]
	v_mfma_f32_32x32x16_bf16 v[16:31], v[170:173], v[200:203], v[16:31]
	v_mfma_f32_32x32x16_bf16 v[0:15], v[174:177], v[200:203], v[0:15]
	s_waitcnt vmcnt(6)
	s_waitcnt lgkmcnt(0)
	s_barrier
	ds_read_b128 v[162:165], v159 offset:32768
	ds_read_b128 v[178:181], v158 offset:24576
	ds_read_b128 v[166:169], v159 offset:34816
	ds_read_b128 v[200:203], v158 offset:26624
	ds_read_b128 v[170:173], v159 offset:36864
	ds_read_b128 v[174:177], v159 offset:38912
	v_mfma_f32_32x32x16_bf16 v[112:127], v[128:131], v[144:147], v[112:127]
	s_mov_b32 m0, s14
	s_nop 0
	global_load_lds_dwordx4 v[204:205], off
	v_lshl_add_u64 v[204:205], v[216:217], 0, v[204:205]
	v_mfma_f32_32x32x16_bf16 v[96:111], v[132:135], v[144:147], v[96:111]
	s_add_u32 m0, s14, 0x1000
	s_nop 0
	global_load_lds_dwordx4 v[206:207], off
	v_lshl_add_u64 v[206:207], v[216:217], 0, v[206:207]
	v_mfma_f32_32x32x16_bf16 v[80:95], v[136:139], v[144:147], v[80:95]
	s_add_u32 m0, s14, 0x2000
	s_nop 0
	global_load_lds_dwordx4 v[208:209], off
	v_lshl_add_u64 v[208:209], v[216:217], 0, v[208:209]
	v_mfma_f32_32x32x16_bf16 v[64:79], v[140:143], v[144:147], v[64:79]
	s_add_u32 m0, s14, 0x3000
	s_nop 0
	global_load_lds_dwordx4 v[210:211], off
	v_lshl_add_u64 v[210:211], v[216:217], 0, v[210:211]
	v_mfma_f32_32x32x16_bf16 v[48:63], v[128:131], v[148:151], v[48:63]
	s_add_u32 m0, s14, 0x4000
	s_nop 0
	global_load_lds_dwordx4 v[212:213], off
	v_lshl_add_u64 v[212:213], v[216:217], 0, v[212:213]
	v_mfma_f32_32x32x16_bf16 v[32:47], v[132:135], v[148:151], v[32:47]
	s_add_u32 m0, s14, 0x5000
	s_nop 0
	global_load_lds_dwordx4 v[214:215], off
	v_lshl_add_u64 v[214:215], v[216:217], 0, v[214:215]
	v_mfma_f32_32x32x16_bf16 v[16:31], v[136:139], v[148:151], v[16:31]
	v_mfma_f32_32x32x16_bf16 v[0:15], v[140:143], v[148:151], v[0:15]
	ds_read_b128 v[128:131], v157 offset:32768
	ds_read_b128 v[144:147], v160 offset:24576
	ds_read_b128 v[132:135], v157 offset:34816
	ds_read_b128 v[148:151], v160 offset:26624
	ds_read_b128 v[136:139], v157 offset:36864
	ds_read_b128 v[140:143], v157 offset:38912
	s_add_u32 s15, s15, 1
	s_cmp_lg_u32 s15, 9
	s_cbranch_scc1 .Lup_dma_loop
	s_waitcnt lgkmcnt(10)
	v_mfma_f32_32x32x16_bf16 v[112:127], v[162:165], v[178:181], v[112:127]
	s_waitcnt lgkmcnt(9)
	v_mfma_f32_32x32x16_bf16 v[96:111], v[166:169], v[178:181], v[96:111]
	s_waitcnt lgkmcnt(7)
	v_mfma_f32_32x32x16_bf16 v[80:95], v[170:173], v[178:181], v[80:95]
	s_waitcnt lgkmcnt(6)
	v_mfma_f32_32x32x16_bf16 v[64:79], v[174:177], v[178:181], v[64:79]
	v_mfma_f32_32x32x16_bf16 v[48:63], v[162:165], v[200:203], v[48:63]
	v_mfma_f32_32x32x16_bf16 v[32:47], v[166:169], v[200:203], v[32:47]
	v_mfma_f32_32x32x16_bf16 v[16:31], v[170:173], v[200:203], v[16:31]
	v_mfma_f32_32x32x16_bf16 v[0:15], v[174:177], v[200:203], v[0:15]
	s_waitcnt vmcnt(6)
	s_waitcnt lgkmcnt(0)
	s_barrier
	ds_read_b128 v[162:165], v159 offset:57344
	ds_read_b128 v[178:181], v158 offset:49152
	ds_read_b128 v[166:169], v159 offset:59392
	ds_read_b128 v[200:203], v158 offset:51200
	ds_read_b128 v[170:173], v159 offset:61440
	ds_read_b128 v[174:177], v159 offset:63488
	v_mfma_f32_32x32x16_bf16 v[112:127], v[128:131], v[144:147], v[112:127]
	s_add_u32 m0, s14, 0x6000
	s_nop 0
	global_load_lds_dwordx4 v[204:205], off
	v_lshl_add_u64 v[204:205], v[216:217], 0, v[204:205]
	v_mfma_f32_32x32x16_bf16 v[96:111], v[132:135], v[144:147], v[96:111]
	s_add_u32 m0, s14, 0x7000
	s_nop 0
	global_load_lds_dwordx4 v[206:207], off
	v_lshl_add_u64 v[206:207], v[216:217], 0, v[206:207]
	v_mfma_f32_32x32x16_bf16 v[80:95], v[136:139], v[144:147], v[80:95]
	s_add_u32 m0, s14, 0x8000
	s_nop 0
	global_load_lds_dwordx4 v[208:209], off
	v_lshl_add_u64 v[208:209], v[216:217], 0, v[208:209]
	v_mfma_f32_32x32x16_bf16 v[64:79], v[140:143], v[144:147], v[64:79]
	s_add_u32 m0, s14, 0x9000
	s_nop 0
	global_load_lds_dwordx4 v[210:211], off
	v_lshl_add_u64 v[210:211], v[216:217], 0, v[210:211]
	v_mfma_f32_32x32x16_bf16 v[48:63], v[128:131], v[148:151], v[48:63]
	s_add_u32 m0, s14, 0xa000
	s_nop 0
	global_load_lds_dwordx4 v[212:213], off
	v_lshl_add_u64 v[212:213], v[216:217], 0, v[212:213]
	v_mfma_f32_32x32x16_bf16 v[32:47], v[132:135], v[148:151], v[32:47]
	s_add_u32 m0, s14, 0xb000
	s_nop 0
	global_load_lds_dwordx4 v[214:215], off
	v_lshl_add_u64 v[214:215], v[216:217], 0, v[214:215]
	v_mfma_f32_32x32x16_bf16 v[16:31], v[136:139], v[148:151], v[16:31]
	v_mfma_f32_32x32x16_bf16 v[0:15], v[140:143], v[148:151], v[0:15]
	ds_read_b128 v[128:131], v157 offset:57344
	ds_read_b128 v[144:147], v160 offset:49152
	ds_read_b128 v[132:135], v157 offset:59392
	ds_read_b128 v[148:151], v160 offset:51200
	ds_read_b128 v[136:139], v157 offset:61440
	ds_read_b128 v[140:143], v157 offset:63488
	s_waitcnt lgkmcnt(10)
	v_mfma_f32_32x32x16_bf16 v[112:127], v[162:165], v[178:181], v[112:127]
	s_waitcnt lgkmcnt(9)
	v_mfma_f32_32x32x16_bf16 v[96:111], v[166:169], v[178:181], v[96:111]
	s_waitcnt lgkmcnt(7)
	v_mfma_f32_32x32x16_bf16 v[80:95], v[170:173], v[178:181], v[80:95]
	s_waitcnt lgkmcnt(6)
	v_mfma_f32_32x32x16_bf16 v[64:79], v[174:177], v[178:181], v[64:79]
	v_mfma_f32_32x32x16_bf16 v[48:63], v[162:165], v[200:203], v[48:63]
	v_mfma_f32_32x32x16_bf16 v[32:47], v[166:169], v[200:203], v[32:47]
	v_mfma_f32_32x32x16_bf16 v[16:31], v[170:173], v[200:203], v[16:31]
	v_mfma_f32_32x32x16_bf16 v[0:15], v[174:177], v[200:203], v[0:15]
	s_waitcnt vmcnt(6)
	s_waitcnt lgkmcnt(0)
	s_barrier
	ds_read_b128 v[162:165], v159 offset:8192
	ds_read_b128 v[178:181], v158
	ds_read_b128 v[166:169], v159 offset:10240
	ds_read_b128 v[200:203], v158 offset:2048
	ds_read_b128 v[170:173], v159 offset:12288
	ds_read_b128 v[174:177], v159 offset:14336
	v_mfma_f32_32x32x16_bf16 v[112:127], v[128:131], v[144:147], v[112:127]
	v_mfma_f32_32x32x16_bf16 v[96:111], v[132:135], v[144:147], v[96:111]
	v_mfma_f32_32x32x16_bf16 v[80:95], v[136:139], v[144:147], v[80:95]
	v_mfma_f32_32x32x16_bf16 v[64:79], v[140:143], v[144:147], v[64:79]
	v_mfma_f32_32x32x16_bf16 v[48:63], v[128:131], v[148:151], v[48:63]
	v_mfma_f32_32x32x16_bf16 v[32:47], v[132:135], v[148:151], v[32:47]
	v_mfma_f32_32x32x16_bf16 v[16:31], v[136:139], v[148:151], v[16:31]
	v_mfma_f32_32x32x16_bf16 v[0:15], v[140:143], v[148:151], v[0:15]
	ds_read_b128 v[128:131], v157 offset:8192
	ds_read_b128 v[144:147], v160
	ds_read_b128 v[132:135], v157 offset:10240
	ds_read_b128 v[148:151], v160 offset:2048
	ds_read_b128 v[136:139], v157 offset:12288
	ds_read_b128 v[140:143], v157 offset:14336
	s_waitcnt lgkmcnt(10)
	v_mfma_f32_32x32x16_bf16 v[112:127], v[162:165], v[178:181], v[112:127]
	s_waitcnt lgkmcnt(9)
	v_mfma_f32_32x32x16_bf16 v[96:111], v[166:169], v[178:181], v[96:111]
	s_waitcnt lgkmcnt(7)
	v_mfma_f32_32x32x16_bf16 v[80:95], v[170:173], v[178:181], v[80:95]
	s_waitcnt lgkmcnt(6)
	v_mfma_f32_32x32x16_bf16 v[64:79], v[174:177], v[178:181], v[64:79]
	v_mfma_f32_32x32x16_bf16 v[48:63], v[162:165], v[200:203], v[48:63]
	v_mfma_f32_32x32x16_bf16 v[32:47], v[166:169], v[200:203], v[32:47]
	v_mfma_f32_32x32x16_bf16 v[16:31], v[170:173], v[200:203], v[16:31]
	v_mfma_f32_32x32x16_bf16 v[0:15], v[174:177], v[200:203], v[0:15]
	s_waitcnt vmcnt(0)
	s_waitcnt lgkmcnt(0)
	s_barrier
	ds_read_b128 v[162:165], v159 offset:32768
	ds_read_b128 v[178:181], v158 offset:24576
	ds_read_b128 v[166:169], v159 offset:34816
	ds_read_b128 v[200:203], v158 offset:26624
	ds_read_b128 v[170:173], v159 offset:36864
	ds_read_b128 v[174:177], v159 offset:38912
	v_mfma_f32_32x32x16_bf16 v[112:127], v[128:131], v[144:147], v[112:127]
	v_mfma_f32_32x32x16_bf16 v[96:111], v[132:135], v[144:147], v[96:111]
	v_mfma_f32_32x32x16_bf16 v[80:95], v[136:139], v[144:147], v[80:95]
	v_mfma_f32_32x32x16_bf16 v[64:79], v[140:143], v[144:147], v[64:79]
	v_mfma_f32_32x32x16_bf16 v[48:63], v[128:131], v[148:151], v[48:63]
	v_mfma_f32_32x32x16_bf16 v[32:47], v[132:135], v[148:151], v[32:47]
	v_mfma_f32_32x32x16_bf16 v[16:31], v[136:139], v[148:151], v[16:31]
	v_mfma_f32_32x32x16_bf16 v[0:15], v[140:143], v[148:151], v[0:15]
	ds_read_b128 v[128:131], v157 offset:32768
	ds_read_b128 v[144:147], v160 offset:24576
	ds_read_b128 v[132:135], v157 offset:34816
	ds_read_b128 v[148:151], v160 offset:26624
	ds_read_b128 v[136:139], v157 offset:36864
	ds_read_b128 v[140:143], v157 offset:38912
	s_waitcnt lgkmcnt(10)
	v_mfma_f32_32x32x16_bf16 v[112:127], v[162:165], v[178:181], v[112:127]
	s_waitcnt lgkmcnt(9)
	v_mfma_f32_32x32x16_bf16 v[96:111], v[166:169], v[178:181], v[96:111]
	s_waitcnt lgkmcnt(7)
	v_mfma_f32_32x32x16_bf16 v[80:95], v[170:173], v[178:181], v[80:95]
	s_waitcnt lgkmcnt(6)
	v_mfma_f32_32x32x16_bf16 v[64:79], v[174:177], v[178:181], v[64:79]
	v_mfma_f32_32x32x16_bf16 v[48:63], v[162:165], v[200:203], v[48:63]
	v_mfma_f32_32x32x16_bf16 v[32:47], v[166:169], v[200:203], v[32:47]
	v_mfma_f32_32x32x16_bf16 v[16:31], v[170:173], v[200:203], v[16:31]
	v_mfma_f32_32x32x16_bf16 v[0:15], v[174:177], v[200:203], v[0:15]
	s_mov_b32 s14, 0xfffffc0
	s_movk_i32 s18, 0x210
	s_lshl_b64 s[4:5], s[4:5], 1
	s_mov_b32 s15, 0
	v_and_b32_e32 v152, 31, v156
	s_waitcnt lgkmcnt(0)
	s_barrier
	v_mfma_f32_32x32x16_bf16 v[48:63], v[128:131], v[148:151], v[48:63]
	v_mfma_f32_32x32x16_bf16 v[0:15], v[140:143], v[148:151], v[0:15]
	s_nop 10
	v_max_f32_e32 v48, v48, v48
	v_max_f32_e32 v49, v49, v49
	v_max_f32_e32 v50, v50, v50
	v_max_f32_e32 v51, v51, v51
	v_max_f32_e32 v52, v52, v52
	v_max_f32_e32 v53, v53, v53
	v_max_f32_e32 v48, 0, v48
	v_mfma_f32_32x32x16_bf16 v[112:127], v[128:131], v[144:147], v[112:127]
	v_lshrrev_b32_e32 v128, 1, v156
	v_lshrrev_b32_e32 v130, 2, v156
	v_and_or_b32 v129, v128, s14, v152
	v_lshlrev_b32_e32 v128, 2, v156
	v_and_b32_e32 v130, 8, v130
	s_movk_i32 s14, 0x100
	v_max_f32_e32 v0, v0, v0
	v_mfma_f32_32x32x16_bf16 v[96:111], v[132:135], v[144:147], v[96:111]
	v_max_f32_e32 v1, v1, v1
	v_max_f32_e32 v2, v2, v2
	v_max_f32_e32 v3, v3, v3
	v_max_f32_e32 v4, v4, v4
	v_max_f32_e32 v5, v5, v5
	v_max_f32_e32 v6, v6, v6
	v_max_f32_e32 v7, v7, v7
	v_mfma_f32_32x32x16_bf16 v[80:95], v[136:139], v[144:147], v[80:95]
	v_and_or_b32 v128, v128, s14, v130
	v_max_f32_e32 v49, 0, v49
	v_max_f32_e32 v50, 0, v50
	v_max_f32_e32 v51, 0, v51
	v_max_f32_e32 v52, 0, v52
	v_max_f32_e32 v53, 0, v53
	v_max_f32_e32 v0, 0, v0
	v_mfma_f32_32x32x16_bf16 v[64:79], v[140:143], v[144:147], v[64:79]
	v_max_f32_e32 v1, 0, v1
	v_max_f32_e32 v2, 0, v2
	v_max_f32_e32 v3, 0, v3
	v_max_f32_e32 v4, 0, v4
	v_max_f32_e32 v5, 0, v5
	v_max_f32_e32 v6, 0, v6
	v_max_f32_e32 v7, 0, v7
	v_mfma_f32_32x32x16_bf16 v[32:47], v[132:135], v[148:151], v[32:47]
	v_max_f32_e32 v8, v8, v8
	v_max_f32_e32 v9, v9, v9
	v_max_f32_e32 v10, v10, v10
	v_max_f32_e32 v11, v11, v11
	v_max_f32_e32 v12, v12, v12
	v_max_f32_e32 v13, v13, v13
	v_max_f32_e32 v14, v14, v14
	v_mfma_f32_32x32x16_bf16 v[16:31], v[136:139], v[148:151], v[16:31]
	v_max_f32_e32 v15, v15, v15
	v_mad_u64_u32 v[128:129], s[14:15], v129, s18, v[128:129]
	v_mul_f32_e64 v48, v48, v48
	v_mul_f32_e64 v49, v49, v49
	v_mul_f32_e64 v50, v50, v50
	v_mul_f32_e64 v51, v51, v51
	v_pk_mul_f32 v[52:53], v[52:53], v[52:53]
	v_pk_mul_f32 v[0:1], v[0:1], v[0:1]
	v_pk_mul_f32 v[2:3], v[2:3], v[2:3]
	v_pk_mul_f32 v[4:5], v[4:5], v[4:5]
	v_pk_mul_f32 v[6:7], v[6:7], v[6:7]
	v_max_f32_e32 v8, 0, v8
	v_max_f32_e32 v9, 0, v9
	v_max_f32_e32 v10, 0, v10
	v_max_f32_e32 v11, 0, v11
	v_max_f32_e32 v12, 0, v12
	v_max_f32_e32 v13, 0, v13
	v_max_f32_e32 v14, 0, v14
	v_max_f32_e32 v15, 0, v15
	v_cvt_pk_bf16_f32 v48, v48, v49
	v_cvt_pk_bf16_f32 v49, v50, v51
	v_cvt_pk_bf16_f32 v50, v52, v53
	v_add_u32_e32 v52, 0x4000, v128
	v_pk_mul_f32 v[8:9], v[8:9], v[8:9]
	v_pk_mul_f32 v[10:11], v[10:11], v[10:11]
	v_pk_mul_f32 v[12:13], v[12:13], v[12:13]
	v_pk_mul_f32 v[14:15], v[14:15], v[14:15]
	v_cvt_pk_bf16_f32 v0, v0, v1
	v_cvt_pk_bf16_f32 v1, v2, v3
	v_cvt_pk_bf16_f32 v2, v4, v5
	v_cvt_pk_bf16_f32 v3, v6, v7
	v_max_f32_e32 v112, v112, v112
	v_max_f32_e32 v113, v113, v113
	v_max_f32_e32 v114, v114, v114
	v_max_f32_e32 v115, v115, v115
	v_max_f32_e32 v116, v116, v116
	v_max_f32_e32 v117, v117, v117
	v_max_f32_e32 v118, v118, v118
	v_max_f32_e32 v119, v119, v119
	v_max_f32_e32 v96, v96, v96
	v_max_f32_e32 v97, v97, v97
	v_max_f32_e32 v98, v98, v98
	v_max_f32_e32 v99, v99, v99
	v_max_f32_e32 v100, v100, v100
	v_max_f32_e32 v101, v101, v101
	v_max_f32_e32 v102, v102, v102
	v_max_f32_e32 v103, v103, v103
	v_max_f32_e32 v80, v80, v80
	v_max_f32_e32 v81, v81, v81
	v_max_f32_e32 v82, v82, v82
	v_max_f32_e32 v83, v83, v83
	v_max_f32_e32 v84, v84, v84
	v_max_f32_e32 v85, v85, v85
	v_max_f32_e32 v86, v86, v86
	v_max_f32_e32 v87, v87, v87
	v_max_f32_e32 v64, v64, v64
	v_max_f32_e32 v65, v65, v65
	v_max_f32_e32 v66, v66, v66
	v_max_f32_e32 v67, v67, v67
	v_max_f32_e32 v68, v68, v68
	v_max_f32_e32 v69, v69, v69
	v_max_f32_e32 v70, v70, v70
	v_max_f32_e32 v71, v71, v71
	v_max_f32_e32 v54, v54, v54
	v_max_f32_e32 v55, v55, v55
	v_max_f32_e32 v32, v32, v32
	v_max_f32_e32 v33, v33, v33
	v_max_f32_e32 v34, v34, v34
	v_max_f32_e32 v35, v35, v35
	v_max_f32_e32 v36, v36, v36
	v_max_f32_e32 v37, v37, v37
	v_max_f32_e32 v38, v38, v38
	v_max_f32_e32 v39, v39, v39
	v_max_f32_e32 v16, v16, v16
	v_max_f32_e32 v17, v17, v17
	v_max_f32_e32 v18, v18, v18
	v_max_f32_e32 v19, v19, v19
	v_max_f32_e32 v20, v20, v20
	v_max_f32_e32 v21, v21, v21
	v_max_f32_e32 v22, v22, v22
	v_max_f32_e32 v23, v23, v23
	ds_write2_b64 v52, v[0:1], v[2:3] offset0:88 offset1:90
	v_cvt_pk_bf16_f32 v0, v8, v9
	v_cvt_pk_bf16_f32 v1, v10, v11
	v_cvt_pk_bf16_f32 v2, v12, v13
	v_cvt_pk_bf16_f32 v3, v14, v15
	v_readlane_b32 s14, v254, 54
	v_max_f32_e32 v112, 0, v112
	v_max_f32_e32 v113, 0, v113
	v_max_f32_e32 v114, 0, v114
	v_max_f32_e32 v115, 0, v115
	v_max_f32_e32 v116, 0, v116
	v_max_f32_e32 v117, 0, v117
	v_max_f32_e32 v118, 0, v118
	v_max_f32_e32 v119, 0, v119
	v_max_f32_e32 v120, v120, v120
	v_max_f32_e32 v121, v121, v121
	v_max_f32_e32 v122, v122, v122
	v_max_f32_e32 v123, v123, v123
	v_max_f32_e32 v124, v124, v124
	v_max_f32_e32 v125, v125, v125
	v_max_f32_e32 v126, v126, v126
	v_max_f32_e32 v127, v127, v127
	v_max_f32_e32 v96, 0, v96
	v_max_f32_e32 v97, 0, v97
	v_max_f32_e32 v98, 0, v98
	v_max_f32_e32 v99, 0, v99
	v_max_f32_e32 v100, 0, v100
	v_max_f32_e32 v101, 0, v101
	v_max_f32_e32 v102, 0, v102
	v_max_f32_e32 v103, 0, v103
	v_max_f32_e32 v104, v104, v104
	v_max_f32_e32 v105, v105, v105
	v_max_f32_e32 v106, v106, v106
	v_max_f32_e32 v107, v107, v107
	v_max_f32_e32 v108, v108, v108
	v_max_f32_e32 v109, v109, v109
	v_max_f32_e32 v110, v110, v110
	v_max_f32_e32 v111, v111, v111
	v_max_f32_e32 v80, 0, v80
	v_max_f32_e32 v81, 0, v81
	v_max_f32_e32 v82, 0, v82
	v_max_f32_e32 v83, 0, v83
	v_max_f32_e32 v84, 0, v84
	v_max_f32_e32 v85, 0, v85
	v_max_f32_e32 v86, 0, v86
	v_max_f32_e32 v87, 0, v87
	v_max_f32_e32 v88, v88, v88
	v_max_f32_e32 v89, v89, v89
	v_max_f32_e32 v90, v90, v90
	v_max_f32_e32 v91, v91, v91
	v_max_f32_e32 v92, v92, v92
	v_max_f32_e32 v93, v93, v93
	v_max_f32_e32 v94, v94, v94
	v_max_f32_e32 v95, v95, v95
	v_max_f32_e32 v64, 0, v64
	v_max_f32_e32 v65, 0, v65
	v_max_f32_e32 v66, 0, v66
	v_max_f32_e32 v67, 0, v67
	v_max_f32_e32 v68, 0, v68
	v_max_f32_e32 v69, 0, v69
	v_max_f32_e32 v70, 0, v70
	v_max_f32_e32 v71, 0, v71
	v_max_f32_e32 v72, v72, v72
	v_max_f32_e32 v73, v73, v73
	v_max_f32_e32 v74, v74, v74
	v_max_f32_e32 v75, v75, v75
	v_max_f32_e32 v76, v76, v76
	v_max_f32_e32 v77, v77, v77
	v_max_f32_e32 v78, v78, v78
	v_max_f32_e32 v79, v79, v79
	v_max_f32_e32 v54, 0, v54
	v_max_f32_e32 v55, 0, v55
	v_max_f32_e32 v56, v56, v56
	v_max_f32_e32 v57, v57, v57
	v_max_f32_e32 v58, v58, v58
	v_max_f32_e32 v59, v59, v59
	v_max_f32_e32 v60, v60, v60
	v_max_f32_e32 v61, v61, v61
	v_max_f32_e32 v62, v62, v62
	v_max_f32_e32 v63, v63, v63
	v_max_f32_e32 v32, 0, v32
	v_max_f32_e32 v33, 0, v33
	v_max_f32_e32 v34, 0, v34
	v_max_f32_e32 v35, 0, v35
	v_max_f32_e32 v36, 0, v36
	v_max_f32_e32 v37, 0, v37
	v_max_f32_e32 v38, 0, v38
	v_max_f32_e32 v39, 0, v39
	v_max_f32_e32 v40, v40, v40
	v_max_f32_e32 v41, v41, v41
	v_max_f32_e32 v42, v42, v42
	v_max_f32_e32 v43, v43, v43
	v_max_f32_e32 v44, v44, v44
	v_max_f32_e32 v45, v45, v45
	v_max_f32_e32 v46, v46, v46
	v_max_f32_e32 v47, v47, v47
	v_max_f32_e32 v16, 0, v16
	v_max_f32_e32 v17, 0, v17
	v_max_f32_e32 v18, 0, v18
	v_max_f32_e32 v19, 0, v19
	v_max_f32_e32 v20, 0, v20
	v_max_f32_e32 v21, 0, v21
	v_max_f32_e32 v22, 0, v22
	v_max_f32_e32 v23, 0, v23
	v_max_f32_e32 v24, v24, v24
	v_max_f32_e32 v25, v25, v25
	v_max_f32_e32 v26, v26, v26
	v_max_f32_e32 v27, v27, v27
	v_max_f32_e32 v28, v28, v28
	v_max_f32_e32 v29, v29, v29
	v_max_f32_e32 v30, v30, v30
	v_max_f32_e32 v31, v31, v31
	ds_write2_b64 v52, v[0:1], v[2:3] offset0:92 offset1:94
	v_lshlrev_b32_e32 v0, 4, v156
	v_readlane_b32 s15, v254, 55
	s_add_u32 s4, s14, s4
	v_pk_mul_f32 v[112:113], v[112:113], v[112:113]
	v_pk_mul_f32 v[114:115], v[114:115], v[114:115]
	v_pk_mul_f32 v[116:117], v[116:117], v[116:117]
	v_pk_mul_f32 v[118:119], v[118:119], v[118:119]
	v_max_f32_e32 v120, 0, v120
	v_max_f32_e32 v121, 0, v121
	v_max_f32_e32 v122, 0, v122
	v_max_f32_e32 v123, 0, v123
	v_max_f32_e32 v124, 0, v124
	v_max_f32_e32 v125, 0, v125
	v_max_f32_e32 v126, 0, v126
	v_max_f32_e32 v127, 0, v127
	v_pk_mul_f32 v[96:97], v[96:97], v[96:97]
	v_pk_mul_f32 v[98:99], v[98:99], v[98:99]
	v_pk_mul_f32 v[100:101], v[100:101], v[100:101]
	v_pk_mul_f32 v[102:103], v[102:103], v[102:103]
	v_max_f32_e32 v104, 0, v104
	v_max_f32_e32 v105, 0, v105
	v_max_f32_e32 v106, 0, v106
	v_max_f32_e32 v107, 0, v107
	v_max_f32_e32 v108, 0, v108
	v_max_f32_e32 v109, 0, v109
	v_max_f32_e32 v110, 0, v110
	v_max_f32_e32 v111, 0, v111
	v_pk_mul_f32 v[80:81], v[80:81], v[80:81]
	v_pk_mul_f32 v[82:83], v[82:83], v[82:83]
	v_pk_mul_f32 v[84:85], v[84:85], v[84:85]
	v_pk_mul_f32 v[86:87], v[86:87], v[86:87]
	v_max_f32_e32 v88, 0, v88
	v_max_f32_e32 v89, 0, v89
	v_max_f32_e32 v90, 0, v90
	v_max_f32_e32 v91, 0, v91
	v_max_f32_e32 v92, 0, v92
	v_max_f32_e32 v93, 0, v93
	v_max_f32_e32 v94, 0, v94
	v_max_f32_e32 v95, 0, v95
	v_pk_mul_f32 v[64:65], v[64:65], v[64:65]
	v_pk_mul_f32 v[66:67], v[66:67], v[66:67]
	v_pk_mul_f32 v[68:69], v[68:69], v[68:69]
	v_pk_mul_f32 v[70:71], v[70:71], v[70:71]
	v_max_f32_e32 v72, 0, v72
	v_max_f32_e32 v73, 0, v73
	v_max_f32_e32 v74, 0, v74
	v_max_f32_e32 v75, 0, v75
	v_max_f32_e32 v76, 0, v76
	v_max_f32_e32 v77, 0, v77
	v_max_f32_e32 v78, 0, v78
	v_max_f32_e32 v79, 0, v79
	v_pk_mul_f32 v[54:55], v[54:55], v[54:55]
	v_max_f32_e32 v56, 0, v56
	v_max_f32_e32 v57, 0, v57
	v_max_f32_e32 v58, 0, v58
	v_max_f32_e32 v59, 0, v59
	v_max_f32_e32 v60, 0, v60
	v_max_f32_e32 v61, 0, v61
	v_max_f32_e32 v62, 0, v62
	v_max_f32_e32 v63, 0, v63
	v_pk_mul_f32 v[32:33], v[32:33], v[32:33]
	v_pk_mul_f32 v[34:35], v[34:35], v[34:35]
	v_pk_mul_f32 v[36:37], v[36:37], v[36:37]
	v_pk_mul_f32 v[38:39], v[38:39], v[38:39]
	v_max_f32_e32 v40, 0, v40
	v_max_f32_e32 v41, 0, v41
	v_max_f32_e32 v42, 0, v42
	v_max_f32_e32 v43, 0, v43
	v_max_f32_e32 v44, 0, v44
	v_max_f32_e32 v45, 0, v45
	v_max_f32_e32 v46, 0, v46
	v_max_f32_e32 v47, 0, v47
	v_pk_mul_f32 v[16:17], v[16:17], v[16:17]
	v_pk_mul_f32 v[18:19], v[18:19], v[18:19]
	v_pk_mul_f32 v[20:21], v[20:21], v[20:21]
	v_pk_mul_f32 v[22:23], v[22:23], v[22:23]
	v_max_f32_e32 v24, 0, v24
	v_max_f32_e32 v25, 0, v25
	v_max_f32_e32 v26, 0, v26
	v_max_f32_e32 v27, 0, v27
	v_max_f32_e32 v28, 0, v28
	v_max_f32_e32 v29, 0, v29
	v_max_f32_e32 v30, 0, v30
	v_max_f32_e32 v31, 0, v31
	v_and_b32_e32 v190, 0x1f0, v0
	s_addc_u32 s5, s15, s5
	v_ashrrev_i32_e32 v2, 5, v156
	v_pk_mul_f32 v[120:121], v[120:121], v[120:121]
	v_pk_mul_f32 v[122:123], v[122:123], v[122:123]
	v_pk_mul_f32 v[124:125], v[124:125], v[124:125]
	v_pk_mul_f32 v[126:127], v[126:127], v[126:127]
	v_cvt_pk_bf16_f32 v112, v112, v113
	v_cvt_pk_bf16_f32 v113, v114, v115
	v_cvt_pk_bf16_f32 v114, v116, v117
	v_cvt_pk_bf16_f32 v115, v118, v119
	v_pk_mul_f32 v[104:105], v[104:105], v[104:105]
	v_pk_mul_f32 v[106:107], v[106:107], v[106:107]
	v_pk_mul_f32 v[108:109], v[108:109], v[108:109]
	v_pk_mul_f32 v[110:111], v[110:111], v[110:111]
	v_cvt_pk_bf16_f32 v96, v96, v97
	v_cvt_pk_bf16_f32 v97, v98, v99
	v_cvt_pk_bf16_f32 v98, v100, v101
	v_cvt_pk_bf16_f32 v99, v102, v103
	v_pk_mul_f32 v[88:89], v[88:89], v[88:89]
	v_pk_mul_f32 v[90:91], v[90:91], v[90:91]
	v_pk_mul_f32 v[92:93], v[92:93], v[92:93]
	v_pk_mul_f32 v[94:95], v[94:95], v[94:95]
	v_cvt_pk_bf16_f32 v80, v80, v81
	v_cvt_pk_bf16_f32 v81, v82, v83
	v_cvt_pk_bf16_f32 v82, v84, v85
	v_cvt_pk_bf16_f32 v83, v86, v87
	v_pk_mul_f32 v[72:73], v[72:73], v[72:73]
	v_pk_mul_f32 v[74:75], v[74:75], v[74:75]
	v_pk_mul_f32 v[76:77], v[76:77], v[76:77]
	v_pk_mul_f32 v[78:79], v[78:79], v[78:79]
	v_cvt_pk_bf16_f32 v64, v64, v65
	v_cvt_pk_bf16_f32 v65, v66, v67
	v_cvt_pk_bf16_f32 v66, v68, v69
	v_cvt_pk_bf16_f32 v67, v70, v71
	v_pk_mul_f32 v[56:57], v[56:57], v[56:57]
	v_pk_mul_f32 v[58:59], v[58:59], v[58:59]
	v_pk_mul_f32 v[60:61], v[60:61], v[60:61]
	v_pk_mul_f32 v[62:63], v[62:63], v[62:63]
	v_cvt_pk_bf16_f32 v51, v54, v55
	v_pk_mul_f32 v[40:41], v[40:41], v[40:41]
	v_pk_mul_f32 v[42:43], v[42:43], v[42:43]
	v_pk_mul_f32 v[44:45], v[44:45], v[44:45]
	v_pk_mul_f32 v[46:47], v[46:47], v[46:47]
	v_cvt_pk_bf16_f32 v32, v32, v33
	v_cvt_pk_bf16_f32 v33, v34, v35
	v_cvt_pk_bf16_f32 v34, v36, v37
	v_cvt_pk_bf16_f32 v35, v38, v39
	v_pk_mul_f32 v[24:25], v[24:25], v[24:25]
	v_pk_mul_f32 v[26:27], v[26:27], v[26:27]
	v_pk_mul_f32 v[28:29], v[28:29], v[28:29]
	v_pk_mul_f32 v[30:31], v[30:31], v[30:31]
	v_cvt_pk_bf16_f32 v16, v16, v17
	v_cvt_pk_bf16_f32 v17, v18, v19
	v_cvt_pk_bf16_f32 v18, v20, v21
	v_cvt_pk_bf16_f32 v19, v22, v23
	v_lshl_add_u64 v[4:5], s[4:5], 0, v[190:191]
	v_mad_u64_u32 v[0:1], s[4:5], v2, s18, v[190:191]
	ds_write2_b64 v128, v[112:113], v[114:115] offset1:2
	v_cvt_pk_bf16_f32 v112, v120, v121
	v_cvt_pk_bf16_f32 v113, v122, v123
	v_cvt_pk_bf16_f32 v114, v124, v125
	v_cvt_pk_bf16_f32 v115, v126, v127
	ds_write2_b64 v128, v[96:97], v[98:99] offset0:8 offset1:10
	v_cvt_pk_bf16_f32 v96, v104, v105
	v_cvt_pk_bf16_f32 v97, v106, v107
	v_cvt_pk_bf16_f32 v98, v108, v109
	v_cvt_pk_bf16_f32 v99, v110, v111
	ds_write2_b64 v128, v[80:81], v[82:83] offset0:16 offset1:18
	v_cvt_pk_bf16_f32 v80, v88, v89
	v_cvt_pk_bf16_f32 v81, v90, v91
	v_cvt_pk_bf16_f32 v82, v92, v93
	v_cvt_pk_bf16_f32 v83, v94, v95
	ds_write2_b64 v128, v[64:65], v[66:67] offset0:24 offset1:26
	v_cvt_pk_bf16_f32 v64, v72, v73
	v_cvt_pk_bf16_f32 v65, v74, v75
	v_cvt_pk_bf16_f32 v66, v76, v77
	v_cvt_pk_bf16_f32 v67, v78, v79
	ds_write2_b64 v52, v[48:49], v[50:51] offset0:64 offset1:66
	v_cvt_pk_bf16_f32 v48, v56, v57
	v_cvt_pk_bf16_f32 v49, v58, v59
	v_cvt_pk_bf16_f32 v50, v60, v61
	v_cvt_pk_bf16_f32 v51, v62, v63
	ds_write2_b64 v52, v[32:33], v[34:35] offset0:72 offset1:74
	v_cvt_pk_bf16_f32 v32, v40, v41
	v_cvt_pk_bf16_f32 v33, v42, v43
	v_cvt_pk_bf16_f32 v34, v44, v45
	v_cvt_pk_bf16_f32 v35, v46, v47
	ds_write2_b64 v52, v[16:17], v[18:19] offset0:80 offset1:82
	v_cvt_pk_bf16_f32 v16, v24, v25
	v_cvt_pk_bf16_f32 v17, v26, v27
	v_cvt_pk_bf16_f32 v18, v28, v29
	v_cvt_pk_bf16_f32 v19, v30, v31
	v_add_u32_e32 v1, s40, v2
	ds_write2_b64 v128, v[112:113], v[114:115] offset0:4 offset1:6
	ds_write2_b64 v128, v[96:97], v[98:99] offset0:12 offset1:14
	ds_write2_b64 v128, v[80:81], v[82:83] offset0:20 offset1:22
	ds_write2_b64 v128, v[64:65], v[66:67] offset0:28 offset1:30
	ds_write2_b64 v52, v[48:49], v[50:51] offset0:68 offset1:70
	ds_write2_b64 v52, v[32:33], v[34:35] offset0:76 offset1:78
	ds_write2_b64 v52, v[16:17], v[18:19] offset0:84 offset1:86
	s_waitcnt lgkmcnt(0)
	s_barrier
	v_mad_i64_i32 v[6:7], s[4:5], v1, s7, v[4:5]
	ds_read_b128 v[0:3], v0
	s_add_i32 s2, s2, 1
	s_waitcnt lgkmcnt(0)
	global_store_dwordx4 v[6:7], v[0:3], off
	s_nop 1
	v_add_u32_e32 v0, 0x100, v156
	v_ashrrev_i32_e32 v2, 5, v0
	v_mad_u64_u32 v[0:1], s[4:5], v2, s18, v[190:191]
	v_add_u32_e32 v1, s40, v2
	v_mad_i64_i32 v[6:7], s[4:5], v1, s7, v[4:5]
	ds_read_b128 v[0:3], v0
	s_waitcnt lgkmcnt(0)
	global_store_dwordx4 v[6:7], v[0:3], off
	s_nop 1
	v_add_u32_e32 v0, 0x200, v156
	v_ashrrev_i32_e32 v2, 5, v0
	v_mad_u64_u32 v[0:1], s[4:5], v2, s18, v[190:191]
	v_add_u32_e32 v1, s40, v2
	v_mad_i64_i32 v[6:7], s[4:5], v1, s7, v[4:5]
	ds_read_b128 v[0:3], v0
	s_waitcnt lgkmcnt(0)
	global_store_dwordx4 v[6:7], v[0:3], off
	s_nop 1
	v_add_u32_e32 v0, 0x300, v156
	v_ashrrev_i32_e32 v2, 5, v0
	v_mad_u64_u32 v[0:1], s[4:5], v2, s18, v[190:191]
	v_add_u32_e32 v1, s40, v2
	v_mad_i64_i32 v[6:7], s[4:5], v1, s7, v[4:5]
	ds_read_b128 v[0:3], v0
	s_waitcnt lgkmcnt(0)
	global_store_dwordx4 v[6:7], v[0:3], off
	s_nop 1
	v_add_u32_e32 v0, 0x400, v156
	v_ashrrev_i32_e32 v2, 5, v0
	v_mad_u64_u32 v[0:1], s[4:5], v2, s18, v[190:191]
	v_add_u32_e32 v1, s40, v2
	v_mad_i64_i32 v[6:7], s[4:5], v1, s7, v[4:5]
	ds_read_b128 v[0:3], v0
	s_waitcnt lgkmcnt(0)
	global_store_dwordx4 v[6:7], v[0:3], off
	s_nop 1
	v_add_u32_e32 v0, 0x500, v156
	v_ashrrev_i32_e32 v2, 5, v0
	v_mad_u64_u32 v[0:1], s[4:5], v2, s18, v[190:191]
	v_add_u32_e32 v1, s40, v2
	v_mad_i64_i32 v[6:7], s[4:5], v1, s7, v[4:5]
	ds_read_b128 v[0:3], v0
	s_waitcnt lgkmcnt(0)
	global_store_dwordx4 v[6:7], v[0:3], off
	s_nop 1
	v_add_u32_e32 v0, 0x600, v156
	v_ashrrev_i32_e32 v2, 5, v0
	v_mad_u64_u32 v[0:1], s[4:5], v2, s18, v[190:191]
	v_add_u32_e32 v1, s40, v2
	v_mad_i64_i32 v[6:7], s[4:5], v1, s7, v[4:5]
	ds_read_b128 v[0:3], v0
	s_waitcnt lgkmcnt(0)
	global_store_dwordx4 v[6:7], v[0:3], off
	s_nop 1
	v_add_u32_e32 v0, 0x700, v156
	v_ashrrev_i32_e32 v2, 5, v0
	v_mad_u64_u32 v[0:1], s[4:5], v2, s18, v[190:191]
	v_add_u32_e32 v1, s40, v2
	v_mad_i64_i32 v[6:7], s[4:5], v1, s7, v[4:5]
	ds_read_b128 v[0:3], v0
	s_waitcnt lgkmcnt(0)
	global_store_dwordx4 v[6:7], v[0:3], off
	s_nop 1
	v_add_u32_e32 v0, 0x800, v156
	v_ashrrev_i32_e32 v2, 5, v0
	v_mad_u64_u32 v[0:1], s[4:5], v2, s18, v[190:191]
	v_add_u32_e32 v1, s40, v2
	v_mad_i64_i32 v[6:7], s[4:5], v1, s7, v[4:5]
	ds_read_b128 v[0:3], v0
	s_waitcnt lgkmcnt(0)
	global_store_dwordx4 v[6:7], v[0:3], off
	s_nop 1
	v_add_u32_e32 v0, 0x900, v156
	v_ashrrev_i32_e32 v2, 5, v0
	v_mad_u64_u32 v[0:1], s[4:5], v2, s18, v[190:191]
	v_add_u32_e32 v1, s40, v2
	v_mad_i64_i32 v[6:7], s[4:5], v1, s7, v[4:5]
	ds_read_b128 v[0:3], v0
	s_waitcnt lgkmcnt(0)
	global_store_dwordx4 v[6:7], v[0:3], off
	s_nop 1
	v_add_u32_e32 v0, 0xa00, v156
	v_ashrrev_i32_e32 v2, 5, v0
	v_mad_u64_u32 v[0:1], s[4:5], v2, s18, v[190:191]
	v_add_u32_e32 v1, s40, v2
	v_mad_i64_i32 v[6:7], s[4:5], v1, s7, v[4:5]
	ds_read_b128 v[0:3], v0
	s_waitcnt lgkmcnt(0)
	global_store_dwordx4 v[6:7], v[0:3], off
	s_nop 1
	v_add_u32_e32 v0, 0xb00, v156
	v_ashrrev_i32_e32 v2, 5, v0
	v_mad_u64_u32 v[0:1], s[4:5], v2, s18, v[190:191]
	v_add_u32_e32 v1, s40, v2
	v_mad_i64_i32 v[6:7], s[4:5], v1, s7, v[4:5]
	ds_read_b128 v[0:3], v0
	s_waitcnt lgkmcnt(0)
	global_store_dwordx4 v[6:7], v[0:3], off
	s_nop 1
	v_add_u32_e32 v0, 0xc00, v156
	v_ashrrev_i32_e32 v2, 5, v0
	v_mad_u64_u32 v[0:1], s[4:5], v2, s18, v[190:191]
	v_add_u32_e32 v1, s40, v2
	v_mad_i64_i32 v[6:7], s[4:5], v1, s7, v[4:5]
	ds_read_b128 v[0:3], v0
	s_waitcnt lgkmcnt(0)
	global_store_dwordx4 v[6:7], v[0:3], off
	s_nop 1
	v_add_u32_e32 v0, 0xd00, v156
	v_ashrrev_i32_e32 v2, 5, v0
	v_mad_u64_u32 v[0:1], s[4:5], v2, s18, v[190:191]
	v_add_u32_e32 v1, s40, v2
	v_mad_i64_i32 v[6:7], s[4:5], v1, s7, v[4:5]
	ds_read_b128 v[0:3], v0
	s_waitcnt lgkmcnt(0)
	global_store_dwordx4 v[6:7], v[0:3], off
	s_nop 1
	v_add_u32_e32 v0, 0xe00, v156
	v_ashrrev_i32_e32 v2, 5, v0
	v_mad_u64_u32 v[0:1], s[4:5], v2, s18, v[190:191]
	v_add_u32_e32 v1, s40, v2
	v_mad_i64_i32 v[6:7], s[4:5], v1, s7, v[4:5]
	ds_read_b128 v[0:3], v0
	s_waitcnt lgkmcnt(0)
	global_store_dwordx4 v[6:7], v[0:3], off
	s_nop 1
	v_add_u32_e32 v0, 0xf00, v156
	v_ashrrev_i32_e32 v2, 5, v0
	v_mad_u64_u32 v[0:1], s[4:5], v2, s18, v[190:191]
	v_add_u32_e32 v1, s40, v2
	v_mad_i64_i32 v[4:5], s[4:5], v1, s7, v[4:5]
	ds_read_b128 v[0:3], v0
	s_mov_b64 s[4:5], 0
	s_waitcnt lgkmcnt(0)
	global_store_dwordx4 v[4:5], v[0:3], off
	s_barrier
	s_branch .LBB0_1060

.LBB0_1125:
	v_add_co_u32_e32 v182, vcc, 0x800, v152
	s_nop 1
	v_addc_co_u32_e32 v183, vcc, 0, v153, vcc
	v_add_co_u32_e32 v204, vcc, s25, v182
	s_nop 1
	v_addc_co_u32_e32 v205, vcc, 0, v183, vcc
	v_add_co_u32_e32 v206, vcc, s27, v182
	s_nop 1
	v_addc_co_u32_e32 v207, vcc, 0, v183, vcc
	v_add_co_u32_e32 v208, vcc, s12, v154
	s_nop 1
	v_addc_co_u32_e32 v209, vcc, 0, v155, vcc
	v_add_co_u32_e32 v210, vcc, s13, v154
	s_nop 1
	v_addc_co_u32_e32 v211, vcc, 0, v155, vcc
	v_add_co_u32_e32 v212, vcc, 0x1e82000, v154
	s_nop 1
	v_addc_co_u32_e32 v213, vcc, 0, v155, vcc
	v_add_co_u32_e32 v214, vcc, 0x1f04000, v154
	s_nop 1
	v_addc_co_u32_e32 v215, vcc, 0, v155, vcc
	v_and_b32_e32 v216, 3, v156
	v_bfe_u32 v217, v156, 4, 2
	v_xor_b32_e32 v218, v216, v217
	v_sub_u32_e32 v218, v218, v216
	v_lshlrev_b32_e32 v218, 4, v218
	v_ashrrev_i32_e32 v219, 31, v218
	v_lshl_add_u64 v[204:205], v[218:219], 0, v[204:205]
	v_lshl_add_u64 v[206:207], v[218:219], 0, v[206:207]
	v_lshl_add_u64 v[208:209], v[218:219], 0, v[208:209]
	v_lshl_add_u64 v[210:211], v[218:219], 0, v[210:211]
	v_lshl_add_u64 v[212:213], v[218:219], 0, v[212:213]
	v_lshl_add_u64 v[214:215], v[218:219], 0, v[214:215]
	v_mov_b32_e32 v216, 64
	v_mov_b32_e32 v217, 0
	v_lshl_add_u64 v[204:205], v[216:217], 1, v[204:205]
	v_lshl_add_u64 v[206:207], v[216:217], 1, v[206:207]
	v_lshl_add_u64 v[208:209], v[216:217], 1, v[208:209]
	v_lshl_add_u64 v[210:211], v[216:217], 1, v[210:211]
	v_lshl_add_u64 v[212:213], v[216:217], 1, v[212:213]
	v_lshl_add_u64 v[214:215], v[216:217], 1, v[214:215]
	v_lshrrev_b32_e32 v246, 6, v156
	v_lshlrev_b32_e32 v246, 10, v246
	s_nop 0
	v_readfirstlane_b32 s14, v246
	ds_read_b128 v[162:165], v157 offset:8192
	ds_read_b128 v[178:181], v161
	ds_read_b128 v[166:169], v157 offset:10240
	ds_read_b128 v[200:203], v161 offset:2048
	ds_read_b128 v[170:173], v157 offset:12288
	ds_read_b128 v[174:177], v157 offset:14336
	s_waitcnt lgkmcnt(4)
	v_mfma_f32_32x32x16_bf16 v[112:127], v[162:165], v[178:181], v[112:127]
	s_waitcnt lgkmcnt(3)
	v_mfma_f32_32x32x16_bf16 v[96:111], v[166:169], v[178:181], v[96:111]
	s_waitcnt lgkmcnt(1)
	v_mfma_f32_32x32x16_bf16 v[80:95], v[170:173], v[178:181], v[80:95]
	s_waitcnt lgkmcnt(0)
	v_mfma_f32_32x32x16_bf16 v[64:79], v[174:177], v[178:181], v[64:79]
	v_mfma_f32_32x32x16_bf16 v[48:63], v[162:165], v[200:203], v[48:63]
	v_mfma_f32_32x32x16_bf16 v[32:47], v[166:169], v[200:203], v[32:47]
	v_mfma_f32_32x32x16_bf16 v[16:31], v[170:173], v[200:203], v[16:31]
	v_mfma_f32_32x32x16_bf16 v[0:15], v[174:177], v[200:203], v[0:15]
	ds_read_b128 v[162:165], v159 offset:8192
	ds_read_b128 v[178:181], v158
	ds_read_b128 v[166:169], v159 offset:10240
	ds_read_b128 v[200:203], v158 offset:2048
	ds_read_b128 v[170:173], v159 offset:12288
	ds_read_b128 v[174:177], v159 offset:14336
	s_waitcnt vmcnt(5)
	ds_write_b128 v160, v[144:147] offset:24576
	s_waitcnt vmcnt(4)
	ds_write_b128 v160, v[148:151] offset:28672
	s_waitcnt vmcnt(3)
	ds_write_b128 v160, v[140:143] offset:32768
	s_waitcnt vmcnt(2)
	ds_write_b128 v160, v[136:139] offset:36864
	s_waitcnt vmcnt(1)
	ds_write_b128 v160, v[132:135] offset:40960
	s_waitcnt vmcnt(0)
	ds_write_b128 v160, v[128:131] offset:45056
	s_add_u32 m0, s14, 0xc000
	s_nop 0
	global_load_lds_dwordx4 v[204:205], off
	v_lshl_add_u64 v[204:205], v[216:217], 0, v[204:205]
	s_add_u32 m0, s14, 0xd000
	s_nop 0
	global_load_lds_dwordx4 v[206:207], off
	v_lshl_add_u64 v[206:207], v[216:217], 0, v[206:207]
	s_add_u32 m0, s14, 0xe000
	s_nop 0
	global_load_lds_dwordx4 v[208:209], off
	v_lshl_add_u64 v[208:209], v[216:217], 0, v[208:209]
	s_add_u32 m0, s14, 0xf000
	s_nop 0
	global_load_lds_dwordx4 v[210:211], off
	v_lshl_add_u64 v[210:211], v[216:217], 0, v[210:211]
	s_add_u32 m0, s14, 0x10000
	s_nop 0
	global_load_lds_dwordx4 v[212:213], off
	v_lshl_add_u64 v[212:213], v[216:217], 0, v[212:213]
	s_add_u32 m0, s14, 0x11000
	s_nop 0
	global_load_lds_dwordx4 v[214:215], off
	v_lshl_add_u64 v[214:215], v[216:217], 0, v[214:215]
	s_waitcnt lgkmcnt(10)
	v_mfma_f32_32x32x16_bf16 v[112:127], v[162:165], v[178:181], v[112:127]
	s_waitcnt lgkmcnt(9)
	v_mfma_f32_32x32x16_bf16 v[96:111], v[166:169], v[178:181], v[96:111]
	s_waitcnt lgkmcnt(7)
	v_mfma_f32_32x32x16_bf16 v[80:95], v[170:173], v[178:181], v[80:95]
	s_waitcnt lgkmcnt(6)
	v_mfma_f32_32x32x16_bf16 v[64:79], v[174:177], v[178:181], v[64:79]
	v_mfma_f32_32x32x16_bf16 v[48:63], v[162:165], v[200:203], v[48:63]
	v_mfma_f32_32x32x16_bf16 v[32:47], v[166:169], v[200:203], v[32:47]
	v_mfma_f32_32x32x16_bf16 v[16:31], v[170:173], v[200:203], v[16:31]
	v_mfma_f32_32x32x16_bf16 v[0:15], v[174:177], v[200:203], v[0:15]
	s_waitcnt lgkmcnt(0)
	s_barrier
	ds_read_b128 v[162:165], v157 offset:32768
	ds_read_b128 v[178:181], v161 offset:24576
	ds_read_b128 v[166:169], v157 offset:34816
	ds_read_b128 v[200:203], v161 offset:26624
	ds_read_b128 v[170:173], v157 offset:36864
	ds_read_b128 v[174:177], v157 offset:38912
	ds_read_b128 v[128:131], v159 offset:32768
	ds_read_b128 v[132:135], v158 offset:24576
	ds_read_b128 v[136:139], v159 offset:34816
	ds_read_b128 v[148:151], v158 offset:26624
	ds_read_b128 v[140:143], v159 offset:36864
	ds_read_b128 v[144:147], v159 offset:38912
	s_mov_b32 m0, s14
	s_nop 0
	global_load_lds_dwordx4 v[204:205], off
	v_lshl_add_u64 v[204:205], v[216:217], 0, v[204:205]
	s_add_u32 m0, s14, 0x1000
	s_nop 0
	global_load_lds_dwordx4 v[206:207], off
	v_lshl_add_u64 v[206:207], v[216:217], 0, v[206:207]
	s_add_u32 m0, s14, 0x2000
	s_nop 0
	global_load_lds_dwordx4 v[208:209], off
	v_lshl_add_u64 v[208:209], v[216:217], 0, v[208:209]
	s_add_u32 m0, s14, 0x3000
	s_nop 0
	global_load_lds_dwordx4 v[210:211], off
	v_lshl_add_u64 v[210:211], v[216:217], 0, v[210:211]
	s_add_u32 m0, s14, 0x4000
	s_nop 0
	global_load_lds_dwordx4 v[212:213], off
	v_lshl_add_u64 v[212:213], v[216:217], 0, v[212:213]
	s_add_u32 m0, s14, 0x5000
	s_nop 0
	global_load_lds_dwordx4 v[214:215], off
	v_lshl_add_u64 v[214:215], v[216:217], 0, v[214:215]
	s_mov_b32 s4, 0
.Ldn_dma_loop:
	s_waitcnt lgkmcnt(10)
	v_mfma_f32_32x32x16_bf16 v[112:127], v[162:165], v[178:181], v[112:127]
	s_waitcnt lgkmcnt(9)
	v_mfma_f32_32x32x16_bf16 v[96:111], v[166:169], v[178:181], v[96:111]
	s_waitcnt lgkmcnt(7)
	v_mfma_f32_32x32x16_bf16 v[80:95], v[170:173], v[178:181], v[80:95]
	s_waitcnt lgkmcnt(6)
	v_mfma_f32_32x32x16_bf16 v[64:79], v[174:177], v[178:181], v[64:79]
	v_mfma_f32_32x32x16_bf16 v[48:63], v[162:165], v[200:203], v[48:63]
	v_mfma_f32_32x32x16_bf16 v[32:47], v[166:169], v[200:203], v[32:47]
	v_mfma_f32_32x32x16_bf16 v[16:31], v[170:173], v[200:203], v[16:31]
	v_mfma_f32_32x32x16_bf16 v[0:15], v[174:177], v[200:203], v[0:15]
	s_waitcnt vmcnt(6)
	s_waitcnt lgkmcnt(0)
	s_barrier
	ds_read_b128 v[162:165], v157 offset:57344
	ds_read_b128 v[178:181], v161 offset:49152
	ds_read_b128 v[166:169], v157 offset:59392
	ds_read_b128 v[200:203], v161 offset:51200
	ds_read_b128 v[170:173], v157 offset:61440
	ds_read_b128 v[174:177], v157 offset:63488
	v_mfma_f32_32x32x16_bf16 v[112:127], v[128:131], v[132:135], v[112:127]
	s_add_u32 m0, s14, 0x6000
	s_nop 0
	global_load_lds_dwordx4 v[204:205], off
	v_lshl_add_u64 v[204:205], v[216:217], 0, v[204:205]
	v_mfma_f32_32x32x16_bf16 v[96:111], v[136:139], v[132:135], v[96:111]
	s_add_u32 m0, s14, 0x7000
	s_nop 0
	global_load_lds_dwordx4 v[206:207], off
	v_lshl_add_u64 v[206:207], v[216:217], 0, v[206:207]
	v_mfma_f32_32x32x16_bf16 v[80:95], v[140:143], v[132:135], v[80:95]
	s_add_u32 m0, s14, 0x8000
	s_nop 0
	global_load_lds_dwordx4 v[208:209], off
	v_lshl_add_u64 v[208:209], v[216:217], 0, v[208:209]
	v_mfma_f32_32x32x16_bf16 v[64:79], v[144:147], v[132:135], v[64:79]
	s_add_u32 m0, s14, 0x9000
	s_nop 0
	global_load_lds_dwordx4 v[210:211], off
	v_lshl_add_u64 v[210:211], v[216:217], 0, v[210:211]
	v_mfma_f32_32x32x16_bf16 v[48:63], v[128:131], v[148:151], v[48:63]
	s_add_u32 m0, s14, 0xa000
	s_nop 0
	global_load_lds_dwordx4 v[212:213], off
	v_lshl_add_u64 v[212:213], v[216:217], 0, v[212:213]
	v_mfma_f32_32x32x16_bf16 v[32:47], v[136:139], v[148:151], v[32:47]
	s_add_u32 m0, s14, 0xb000
	s_nop 0
	global_load_lds_dwordx4 v[214:215], off
	v_lshl_add_u64 v[214:215], v[216:217], 0, v[214:215]
	v_mfma_f32_32x32x16_bf16 v[16:31], v[140:143], v[148:151], v[16:31]
	v_mfma_f32_32x32x16_bf16 v[0:15], v[144:147], v[148:151], v[0:15]
	ds_read_b128 v[128:131], v159 offset:57344
	ds_read_b128 v[132:135], v158 offset:49152
	ds_read_b128 v[136:139], v159 offset:59392
	ds_read_b128 v[148:151], v158 offset:51200
	ds_read_b128 v[140:143], v159 offset:61440
	ds_read_b128 v[144:147], v159 offset:63488
	s_waitcnt lgkmcnt(10)
	v_mfma_f32_32x32x16_bf16 v[112:127], v[162:165], v[178:181], v[112:127]
	s_waitcnt lgkmcnt(9)
	v_mfma_f32_32x32x16_bf16 v[96:111], v[166:169], v[178:181], v[96:111]
	s_waitcnt lgkmcnt(7)
	v_mfma_f32_32x32x16_bf16 v[80:95], v[170:173], v[178:181], v[80:95]
	s_waitcnt lgkmcnt(6)
	v_mfma_f32_32x32x16_bf16 v[64:79], v[174:177], v[178:181], v[64:79]
	v_mfma_f32_32x32x16_bf16 v[48:63], v[162:165], v[200:203], v[48:63]
	v_mfma_f32_32x32x16_bf16 v[32:47], v[166:169], v[200:203], v[32:47]
	v_mfma_f32_32x32x16_bf16 v[16:31], v[170:173], v[200:203], v[16:31]
	v_mfma_f32_32x32x16_bf16 v[0:15], v[174:177], v[200:203], v[0:15]
	s_waitcnt vmcnt(6)
	s_waitcnt lgkmcnt(0)
	s_barrier
	ds_read_b128 v[162:165], v157 offset:8192
	ds_read_b128 v[178:181], v161
	ds_read_b128 v[166:169], v157 offset:10240
	ds_read_b128 v[200:203], v161 offset:2048
	ds_read_b128 v[170:173], v157 offset:12288
	ds_read_b128 v[174:177], v157 offset:14336
	v_mfma_f32_32x32x16_bf16 v[112:127], v[128:131], v[132:135], v[112:127]
	s_add_u32 m0, s14, 0xc000
	s_nop 0
	global_load_lds_dwordx4 v[204:205], off
	v_lshl_add_u64 v[204:205], v[216:217], 0, v[204:205]
	v_mfma_f32_32x32x16_bf16 v[96:111], v[136:139], v[132:135], v[96:111]
	s_add_u32 m0, s14, 0xd000
	s_nop 0
	global_load_lds_dwordx4 v[206:207], off
	v_lshl_add_u64 v[206:207], v[216:217], 0, v[206:207]
	v_mfma_f32_32x32x16_bf16 v[80:95], v[140:143], v[132:135], v[80:95]
	s_add_u32 m0, s14, 0xe000
	s_nop 0
	global_load_lds_dwordx4 v[208:209], off
	v_lshl_add_u64 v[208:209], v[216:217], 0, v[208:209]
	v_mfma_f32_32x32x16_bf16 v[64:79], v[144:147], v[132:135], v[64:79]
	s_add_u32 m0, s14, 0xf000
	s_nop 0
	global_load_lds_dwordx4 v[210:211], off
	v_lshl_add_u64 v[210:211], v[216:217], 0, v[210:211]
	v_mfma_f32_32x32x16_bf16 v[48:63], v[128:131], v[148:151], v[48:63]
	s_add_u32 m0, s14, 0x10000
	s_nop 0
	global_load_lds_dwordx4 v[212:213], off
	v_lshl_add_u64 v[212:213], v[216:217], 0, v[212:213]
	v_mfma_f32_32x32x16_bf16 v[32:47], v[136:139], v[148:151], v[32:47]
	s_add_u32 m0, s14, 0x11000
	s_nop 0
	global_load_lds_dwordx4 v[214:215], off
	v_lshl_add_u64 v[214:215], v[216:217], 0, v[214:215]
	v_mfma_f32_32x32x16_bf16 v[16:31], v[140:143], v[148:151], v[16:31]
	v_mfma_f32_32x32x16_bf16 v[0:15], v[144:147], v[148:151], v[0:15]
	ds_read_b128 v[128:131], v159 offset:8192
	ds_read_b128 v[132:135], v158
	ds_read_b128 v[136:139], v159 offset:10240
	ds_read_b128 v[148:151], v158 offset:2048
	ds_read_b128 v[140:143], v159 offset:12288
	ds_read_b128 v[144:147], v159 offset:14336
	s_waitcnt lgkmcnt(10)
	v_mfma_f32_32x32x16_bf16 v[112:127], v[162:165], v[178:181], v[112:127]
	s_waitcnt lgkmcnt(9)
	v_mfma_f32_32x32x16_bf16 v[96:111], v[166:169], v[178:181], v[96:111]
	s_waitcnt lgkmcnt(7)
	v_mfma_f32_32x32x16_bf16 v[80:95], v[170:173], v[178:181], v[80:95]
	s_waitcnt lgkmcnt(6)
	v_mfma_f32_32x32x16_bf16 v[64:79], v[174:177], v[178:181], v[64:79]
	v_mfma_f32_32x32x16_bf16 v[48:63], v[162:165], v[200:203], v[48:63]
	v_mfma_f32_32x32x16_bf16 v[32:47], v[166:169], v[200:203], v[32:47]
	v_mfma_f32_32x32x16_bf16 v[16:31], v[170:173], v[200:203], v[16:31]
	v_mfma_f32_32x32x16_bf16 v[0:15], v[174:177], v[200:203], v[0:15]
	s_waitcnt vmcnt(6)
	s_waitcnt lgkmcnt(0)
	s_barrier
	ds_read_b128 v[162:165], v157 offset:32768
	ds_read_b128 v[178:181], v161 offset:24576
	ds_read_b128 v[166:169], v157 offset:34816
	ds_read_b128 v[200:203], v161 offset:26624
	ds_read_b128 v[170:173], v157 offset:36864
	ds_read_b128 v[174:177], v157 offset:38912
	v_mfma_f32_32x32x16_bf16 v[112:127], v[128:131], v[132:135], v[112:127]
	s_mov_b32 m0, s14
	s_nop 0
	global_load_lds_dwordx4 v[204:205], off
	v_lshl_add_u64 v[204:205], v[216:217], 0, v[204:205]
	v_mfma_f32_32x32x16_bf16 v[96:111], v[136:139], v[132:135], v[96:111]
	s_add_u32 m0, s14, 0x1000
	s_nop 0
	global_load_lds_dwordx4 v[206:207], off
	v_lshl_add_u64 v[206:207], v[216:217], 0, v[206:207]
	v_mfma_f32_32x32x16_bf16 v[80:95], v[140:143], v[132:135], v[80:95]
	s_add_u32 m0, s14, 0x2000
	s_nop 0
	global_load_lds_dwordx4 v[208:209], off
	v_lshl_add_u64 v[208:209], v[216:217], 0, v[208:209]
	v_mfma_f32_32x32x16_bf16 v[64:79], v[144:147], v[132:135], v[64:79]
	s_add_u32 m0, s14, 0x3000
	s_nop 0
	global_load_lds_dwordx4 v[210:211], off
	v_lshl_add_u64 v[210:211], v[216:217], 0, v[210:211]
	v_mfma_f32_32x32x16_bf16 v[48:63], v[128:131], v[148:151], v[48:63]
	s_add_u32 m0, s14, 0x4000
	s_nop 0
	global_load_lds_dwordx4 v[212:213], off
	v_lshl_add_u64 v[212:213], v[216:217], 0, v[212:213]
	v_mfma_f32_32x32x16_bf16 v[32:47], v[136:139], v[148:151], v[32:47]
	s_add_u32 m0, s14, 0x5000
	s_nop 0
	global_load_lds_dwordx4 v[214:215], off
	v_lshl_add_u64 v[214:215], v[216:217], 0, v[214:215]
	v_mfma_f32_32x32x16_bf16 v[16:31], v[140:143], v[148:151], v[16:31]
	v_mfma_f32_32x32x16_bf16 v[0:15], v[144:147], v[148:151], v[0:15]
	ds_read_b128 v[128:131], v159 offset:32768
	ds_read_b128 v[132:135], v158 offset:24576
	ds_read_b128 v[136:139], v159 offset:34816
	ds_read_b128 v[148:151], v158 offset:26624
	ds_read_b128 v[140:143], v159 offset:36864
	ds_read_b128 v[144:147], v159 offset:38912
	s_add_u32 s4, s4, 1
	s_cmp_lg_u32 s4, 41
	s_cbranch_scc1 .Ldn_dma_loop
	s_waitcnt lgkmcnt(10)
	v_mfma_f32_32x32x16_bf16 v[112:127], v[162:165], v[178:181], v[112:127]
	s_waitcnt lgkmcnt(9)
	v_mfma_f32_32x32x16_bf16 v[96:111], v[166:169], v[178:181], v[96:111]
	s_waitcnt lgkmcnt(7)
	v_mfma_f32_32x32x16_bf16 v[80:95], v[170:173], v[178:181], v[80:95]
	s_waitcnt lgkmcnt(6)
	v_mfma_f32_32x32x16_bf16 v[64:79], v[174:177], v[178:181], v[64:79]
	v_mfma_f32_32x32x16_bf16 v[48:63], v[162:165], v[200:203], v[48:63]
	v_mfma_f32_32x32x16_bf16 v[32:47], v[166:169], v[200:203], v[32:47]
	v_mfma_f32_32x32x16_bf16 v[16:31], v[170:173], v[200:203], v[16:31]
	v_mfma_f32_32x32x16_bf16 v[0:15], v[174:177], v[200:203], v[0:15]
	s_waitcnt vmcnt(6)
	s_waitcnt lgkmcnt(0)
	s_barrier
	ds_read_b128 v[162:165], v157 offset:57344
	ds_read_b128 v[178:181], v161 offset:49152
	ds_read_b128 v[166:169], v157 offset:59392
	ds_read_b128 v[200:203], v161 offset:51200
	ds_read_b128 v[170:173], v157 offset:61440
	ds_read_b128 v[174:177], v157 offset:63488
	v_mfma_f32_32x32x16_bf16 v[112:127], v[128:131], v[132:135], v[112:127]
	s_add_u32 m0, s14, 0x6000
	s_nop 0
	global_load_lds_dwordx4 v[204:205], off
	v_lshl_add_u64 v[204:205], v[216:217], 0, v[204:205]
	v_mfma_f32_32x32x16_bf16 v[96:111], v[136:139], v[132:135], v[96:111]
	s_add_u32 m0, s14, 0x7000
	s_nop 0
	global_load_lds_dwordx4 v[206:207], off
	v_lshl_add_u64 v[206:207], v[216:217], 0, v[206:207]
	v_mfma_f32_32x32x16_bf16 v[80:95], v[140:143], v[132:135], v[80:95]
	s_add_u32 m0, s14, 0x8000
	s_nop 0
	global_load_lds_dwordx4 v[208:209], off
	v_lshl_add_u64 v[208:209], v[216:217], 0, v[208:209]
	v_mfma_f32_32x32x16_bf16 v[64:79], v[144:147], v[132:135], v[64:79]
	s_add_u32 m0, s14, 0x9000
	s_nop 0
	global_load_lds_dwordx4 v[210:211], off
	v_lshl_add_u64 v[210:211], v[216:217], 0, v[210:211]
	v_mfma_f32_32x32x16_bf16 v[48:63], v[128:131], v[148:151], v[48:63]
	s_add_u32 m0, s14, 0xa000
	s_nop 0
	global_load_lds_dwordx4 v[212:213], off
	v_lshl_add_u64 v[212:213], v[216:217], 0, v[212:213]
	v_mfma_f32_32x32x16_bf16 v[32:47], v[136:139], v[148:151], v[32:47]
	s_add_u32 m0, s14, 0xb000
	s_nop 0
	global_load_lds_dwordx4 v[214:215], off
	v_lshl_add_u64 v[214:215], v[216:217], 0, v[214:215]
	v_mfma_f32_32x32x16_bf16 v[16:31], v[140:143], v[148:151], v[16:31]
	v_mfma_f32_32x32x16_bf16 v[0:15], v[144:147], v[148:151], v[0:15]
	ds_read_b128 v[128:131], v159 offset:57344
	ds_read_b128 v[132:135], v158 offset:49152
	ds_read_b128 v[136:139], v159 offset:59392
	ds_read_b128 v[148:151], v158 offset:51200
	ds_read_b128 v[140:143], v159 offset:61440
	ds_read_b128 v[144:147], v159 offset:63488
	s_waitcnt lgkmcnt(10)
	v_mfma_f32_32x32x16_bf16 v[112:127], v[162:165], v[178:181], v[112:127]
	s_waitcnt lgkmcnt(9)
	v_mfma_f32_32x32x16_bf16 v[96:111], v[166:169], v[178:181], v[96:111]
	s_waitcnt lgkmcnt(7)
	v_mfma_f32_32x32x16_bf16 v[80:95], v[170:173], v[178:181], v[80:95]
	s_waitcnt lgkmcnt(6)
	v_mfma_f32_32x32x16_bf16 v[64:79], v[174:177], v[178:181], v[64:79]
	v_mfma_f32_32x32x16_bf16 v[48:63], v[162:165], v[200:203], v[48:63]
	v_mfma_f32_32x32x16_bf16 v[32:47], v[166:169], v[200:203], v[32:47]
	v_mfma_f32_32x32x16_bf16 v[16:31], v[170:173], v[200:203], v[16:31]
	v_mfma_f32_32x32x16_bf16 v[0:15], v[174:177], v[200:203], v[0:15]
	s_waitcnt vmcnt(6)
	s_waitcnt lgkmcnt(0)
	s_barrier
	ds_read_b128 v[162:165], v157 offset:8192
	ds_read_b128 v[178:181], v161
	ds_read_b128 v[166:169], v157 offset:10240
	ds_read_b128 v[200:203], v161 offset:2048
	ds_read_b128 v[170:173], v157 offset:12288
	ds_read_b128 v[174:177], v157 offset:14336
	v_mfma_f32_32x32x16_bf16 v[112:127], v[128:131], v[132:135], v[112:127]
	v_mfma_f32_32x32x16_bf16 v[96:111], v[136:139], v[132:135], v[96:111]
	v_mfma_f32_32x32x16_bf16 v[80:95], v[140:143], v[132:135], v[80:95]
	v_mfma_f32_32x32x16_bf16 v[64:79], v[144:147], v[132:135], v[64:79]
	v_mfma_f32_32x32x16_bf16 v[48:63], v[128:131], v[148:151], v[48:63]
	v_mfma_f32_32x32x16_bf16 v[32:47], v[136:139], v[148:151], v[32:47]
	v_mfma_f32_32x32x16_bf16 v[16:31], v[140:143], v[148:151], v[16:31]
	v_mfma_f32_32x32x16_bf16 v[0:15], v[144:147], v[148:151], v[0:15]
	ds_read_b128 v[128:131], v159 offset:8192
	ds_read_b128 v[132:135], v158
	ds_read_b128 v[136:139], v159 offset:10240
	ds_read_b128 v[148:151], v158 offset:2048
	ds_read_b128 v[140:143], v159 offset:12288
	ds_read_b128 v[144:147], v159 offset:14336
	s_waitcnt lgkmcnt(10)
	v_mfma_f32_32x32x16_bf16 v[112:127], v[162:165], v[178:181], v[112:127]
	s_waitcnt lgkmcnt(9)
	v_mfma_f32_32x32x16_bf16 v[96:111], v[166:169], v[178:181], v[96:111]
	s_waitcnt lgkmcnt(7)
	v_mfma_f32_32x32x16_bf16 v[80:95], v[170:173], v[178:181], v[80:95]
	s_waitcnt lgkmcnt(6)
	v_mfma_f32_32x32x16_bf16 v[64:79], v[174:177], v[178:181], v[64:79]
	v_mfma_f32_32x32x16_bf16 v[48:63], v[162:165], v[200:203], v[48:63]
	v_mfma_f32_32x32x16_bf16 v[32:47], v[166:169], v[200:203], v[32:47]
	v_mfma_f32_32x32x16_bf16 v[16:31], v[170:173], v[200:203], v[16:31]
	v_mfma_f32_32x32x16_bf16 v[0:15], v[174:177], v[200:203], v[0:15]
	s_waitcnt vmcnt(0)
	s_waitcnt lgkmcnt(0)
	s_barrier
	ds_read_b128 v[162:165], v157 offset:32768
	ds_read_b128 v[178:181], v161 offset:24576
	ds_read_b128 v[166:169], v157 offset:34816
	ds_read_b128 v[200:203], v161 offset:26624
	ds_read_b128 v[170:173], v157 offset:36864
	ds_read_b128 v[174:177], v157 offset:38912
	v_mfma_f32_32x32x16_bf16 v[112:127], v[128:131], v[132:135], v[112:127]
	v_mfma_f32_32x32x16_bf16 v[96:111], v[136:139], v[132:135], v[96:111]
	v_mfma_f32_32x32x16_bf16 v[80:95], v[140:143], v[132:135], v[80:95]
	v_mfma_f32_32x32x16_bf16 v[64:79], v[144:147], v[132:135], v[64:79]
	v_mfma_f32_32x32x16_bf16 v[48:63], v[128:131], v[148:151], v[48:63]
	v_mfma_f32_32x32x16_bf16 v[32:47], v[136:139], v[148:151], v[32:47]
	v_mfma_f32_32x32x16_bf16 v[16:31], v[140:143], v[148:151], v[16:31]
	v_mfma_f32_32x32x16_bf16 v[0:15], v[144:147], v[148:151], v[0:15]
	ds_read_b128 v[128:131], v159 offset:32768
	ds_read_b128 v[132:135], v158 offset:24576
	ds_read_b128 v[136:139], v159 offset:34816
	ds_read_b128 v[148:151], v158 offset:26624
	ds_read_b128 v[140:143], v159 offset:36864
	ds_read_b128 v[144:147], v159 offset:38912
	s_waitcnt lgkmcnt(10)
	v_mfma_f32_32x32x16_bf16 v[112:127], v[162:165], v[178:181], v[112:127]
	s_waitcnt lgkmcnt(9)
	v_mfma_f32_32x32x16_bf16 v[96:111], v[166:169], v[178:181], v[96:111]
	s_waitcnt lgkmcnt(7)
	v_mfma_f32_32x32x16_bf16 v[80:95], v[170:173], v[178:181], v[80:95]
	s_waitcnt lgkmcnt(6)
	v_mfma_f32_32x32x16_bf16 v[64:79], v[174:177], v[178:181], v[64:79]
	v_mfma_f32_32x32x16_bf16 v[48:63], v[162:165], v[200:203], v[48:63]
	v_mfma_f32_32x32x16_bf16 v[32:47], v[166:169], v[200:203], v[32:47]
	v_mfma_f32_32x32x16_bf16 v[16:31], v[170:173], v[200:203], v[16:31]
	v_mfma_f32_32x32x16_bf16 v[0:15], v[174:177], v[200:203], v[0:15]
	s_mov_b32 s14, 0x1f04000
	s_mov_b32 s5, 0
	s_waitcnt lgkmcnt(0)
	s_barrier
	v_mfma_f32_32x32x16_bf16 v[112:127], v[128:131], v[132:135], v[112:127]
	v_mfma_f32_32x32x16_bf16 v[96:111], v[136:139], v[132:135], v[96:111]
	v_mfma_f32_32x32x16_bf16 v[80:95], v[140:143], v[132:135], v[80:95]
	v_mfma_f32_32x32x16_bf16 v[64:79], v[144:147], v[132:135], v[64:79]
	v_mfma_f32_32x32x16_bf16 v[48:63], v[128:131], v[148:151], v[48:63]
	v_ashrrev_i32_e32 v128, 1, v156
	v_and_b32_e32 v128, 0xffffffc0, v128
	v_add_u32_e32 v128, s40, v128
	v_and_or_b32 v134, v156, 31, v128
	v_cmp_lt_i32_e32 vcc, s57, v134
	v_mfma_f32_32x32x16_bf16 v[32:47], v[136:139], v[148:151], v[32:47]
	v_mfma_f32_32x32x16_bf16 v[16:31], v[140:143], v[148:151], v[16:31]
	v_mfma_f32_32x32x16_bf16 v[0:15], v[144:147], v[148:151], v[0:15]
	s_and_saveexec_b64 s[4:5], vcc
	s_xor_b64 s[4:5], exec, s[4:5]
	v_add_u32_e32 v190, 0xffffc000, v134
	v_mov_b64_e32 v[128:129], v[190:191]
	s_or_saveexec_b64 s[4:5], s[4:5]
	v_mov_b32_e32 v132, 0
	v_mov_b64_e32 v[130:131], 0
	s_xor_b64 exec, exec, s[4:5]
	v_add_u32_e32 v128, s21, v134
	v_ashrrev_i32_e32 v129, 12, v128
	v_add_u32_e32 v132, 1, v129
	v_ashrrev_i32_e32 v129, 31, v128
	v_mov_b64_e32 v[130:131], 0x400000
	s_or_b64 exec, exec, s[4:5]
	v_lshlrev_b32_e32 v131, 1, v156
	v_lshrrev_b32_e32 v133, 3, v156
	s_lshl_b32 s4, s23, 8
	v_and_b32_e32 v131, 0x80, v131
	v_and_b32_e32 v133, 4, v133
	v_or3_b32 v136, v133, v131, s4
	v_readlane_b32 s4, v255, 18
	v_readlane_b32 s5, v255, 19
	v_readlane_b32 s40, v252, 4
	v_add_u32_e32 v131, s2, v132
	v_mov_b64_e32 v[132:133], s[4:5]
	v_lshlrev_b32_e32 v190, 2, v130
	v_readlane_b32 s52, v252, 16
	v_readlane_b32 s53, v252, 17
	v_mad_i64_i32 v[132:133], s[4:5], v131, s88, v[132:133]
	s_nop 0
	v_lshl_add_u64 v[130:131], s[52:53], 0, v[190:191]
	v_lshlrev_b64 v[128:129], 12, v[128:129]
	v_ashrrev_i32_e32 v137, 31, v136
	v_lshl_add_u64 v[130:131], v[130:131], 0, v[128:129]
	v_lshlrev_b64 v[128:129], 2, v[136:137]
	v_lshl_add_u64 v[130:131], v[130:131], 0, v[128:129]
	v_lshl_add_u64 v[132:133], v[132:133], 0, v[128:129]
	global_load_dwordx4 v[136:139], v[130:131], off
	global_load_dwordx4 v[140:143], v[132:133], off
	v_readlane_b32 s41, v252, 5
	v_readlane_b32 s42, v252, 6
	v_readlane_b32 s43, v252, 7
	v_readlane_b32 s44, v252, 8
	v_readlane_b32 s45, v252, 9
	v_readlane_b32 s46, v252, 10
	v_readlane_b32 s47, v252, 11
	v_readlane_b32 s48, v252, 12
	v_readlane_b32 s49, v252, 13
	v_readlane_b32 s50, v252, 14
	v_readlane_b32 s51, v252, 15
	v_readlane_b32 s54, v252, 18
	v_readlane_b32 s55, v252, 19
	s_waitcnt vmcnt(0)
	v_pk_fma_f32 v[112:113], v[112:113], v[140:141], v[136:137]
	v_pk_fma_f32 v[114:115], v[114:115], v[142:143], v[138:139]
	global_store_dwordx4 v[130:131], v[112:115], off
	global_load_dwordx4 v[112:115], v[130:131], off offset:32
	s_nop 0
	global_load_dwordx4 v[136:139], v[132:133], off offset:32
	s_waitcnt vmcnt(0)
	v_pk_fma_f32 v[112:113], v[116:117], v[136:137], v[112:113]
	v_pk_fma_f32 v[114:115], v[118:119], v[138:139], v[114:115]
	global_store_dwordx4 v[130:131], v[112:115], off offset:32
	global_load_dwordx4 v[112:115], v[130:131], off offset:64
	s_nop 0
	global_load_dwordx4 v[116:119], v[132:133], off offset:64
	s_waitcnt vmcnt(0)
	v_pk_fma_f32 v[112:113], v[120:121], v[116:117], v[112:113]
	v_pk_fma_f32 v[114:115], v[122:123], v[118:119], v[114:115]
	global_store_dwordx4 v[130:131], v[112:115], off offset:64
	global_load_dwordx4 v[112:115], v[130:131], off offset:96
	s_nop 0
	global_load_dwordx4 v[116:119], v[132:133], off offset:96
	s_waitcnt vmcnt(0)
	v_pk_fma_f32 v[112:113], v[124:125], v[116:117], v[112:113]
	v_pk_fma_f32 v[114:115], v[126:127], v[118:119], v[114:115]
	global_store_dwordx4 v[130:131], v[112:115], off offset:96
	global_load_dwordx4 v[112:115], v[130:131], off offset:128
	s_nop 0
	global_load_dwordx4 v[116:119], v[132:133], off offset:128
	s_waitcnt vmcnt(0)
	v_pk_fma_f32 v[96:97], v[96:97], v[116:117], v[112:113]
	v_pk_fma_f32 v[98:99], v[98:99], v[118:119], v[114:115]
	global_store_dwordx4 v[130:131], v[96:99], off offset:128
	global_load_dwordx4 v[96:99], v[130:131], off offset:160
	s_nop 0
	global_load_dwordx4 v[112:115], v[132:133], off offset:160
	s_waitcnt vmcnt(0)
	v_pk_fma_f32 v[96:97], v[100:101], v[112:113], v[96:97]
	v_pk_fma_f32 v[98:99], v[102:103], v[114:115], v[98:99]
	global_store_dwordx4 v[130:131], v[96:99], off offset:160
	global_load_dwordx4 v[96:99], v[130:131], off offset:192
	s_nop 0
	global_load_dwordx4 v[100:103], v[132:133], off offset:192
	s_waitcnt vmcnt(0)
	v_pk_fma_f32 v[96:97], v[104:105], v[100:101], v[96:97]
	v_pk_fma_f32 v[98:99], v[106:107], v[102:103], v[98:99]
	global_store_dwordx4 v[130:131], v[96:99], off offset:192
	global_load_dwordx4 v[96:99], v[130:131], off offset:224
	s_nop 0
	global_load_dwordx4 v[100:103], v[132:133], off offset:224
	s_waitcnt vmcnt(0)
	v_pk_fma_f32 v[96:97], v[108:109], v[100:101], v[96:97]
	v_pk_fma_f32 v[98:99], v[110:111], v[102:103], v[98:99]
	global_store_dwordx4 v[130:131], v[96:99], off offset:224
	global_load_dwordx4 v[96:99], v[130:131], off offset:256
	s_nop 0
	global_load_dwordx4 v[100:103], v[132:133], off offset:256
	s_waitcnt vmcnt(0)
	v_pk_fma_f32 v[80:81], v[80:81], v[100:101], v[96:97]
	v_pk_fma_f32 v[82:83], v[82:83], v[102:103], v[98:99]
	global_store_dwordx4 v[130:131], v[80:83], off offset:256
	global_load_dwordx4 v[80:83], v[130:131], off offset:288
	s_nop 0
	global_load_dwordx4 v[96:99], v[132:133], off offset:288
	s_waitcnt vmcnt(0)
	v_pk_fma_f32 v[80:81], v[84:85], v[96:97], v[80:81]
	v_pk_fma_f32 v[82:83], v[86:87], v[98:99], v[82:83]
	global_store_dwordx4 v[130:131], v[80:83], off offset:288
	global_load_dwordx4 v[80:83], v[130:131], off offset:320
	s_nop 0
	global_load_dwordx4 v[84:87], v[132:133], off offset:320
	s_waitcnt vmcnt(0)
	v_pk_fma_f32 v[80:81], v[88:89], v[84:85], v[80:81]
	v_pk_fma_f32 v[82:83], v[90:91], v[86:87], v[82:83]
	global_store_dwordx4 v[130:131], v[80:83], off offset:320
	global_load_dwordx4 v[80:83], v[130:131], off offset:352
	s_nop 0
	global_load_dwordx4 v[84:87], v[132:133], off offset:352
	s_waitcnt vmcnt(0)
	v_pk_fma_f32 v[80:81], v[92:93], v[84:85], v[80:81]
	v_pk_fma_f32 v[82:83], v[94:95], v[86:87], v[82:83]
	global_store_dwordx4 v[130:131], v[80:83], off offset:352
	global_load_dwordx4 v[80:83], v[130:131], off offset:384
	s_nop 0
	global_load_dwordx4 v[84:87], v[132:133], off offset:384
	s_waitcnt vmcnt(0)
	v_pk_fma_f32 v[64:65], v[64:65], v[84:85], v[80:81]
	v_pk_fma_f32 v[66:67], v[66:67], v[86:87], v[82:83]
	global_store_dwordx4 v[130:131], v[64:67], off offset:384
	global_load_dwordx4 v[64:67], v[130:131], off offset:416
	s_nop 0
	global_load_dwordx4 v[80:83], v[132:133], off offset:416
	s_waitcnt vmcnt(0)
	v_pk_fma_f32 v[64:65], v[68:69], v[80:81], v[64:65]
	v_pk_fma_f32 v[66:67], v[70:71], v[82:83], v[66:67]
	global_store_dwordx4 v[130:131], v[64:67], off offset:416
	global_load_dwordx4 v[64:67], v[130:131], off offset:448
	s_nop 0
	global_load_dwordx4 v[68:71], v[132:133], off offset:448
	s_waitcnt vmcnt(0)
	v_pk_fma_f32 v[64:65], v[72:73], v[68:69], v[64:65]
	v_pk_fma_f32 v[66:67], v[74:75], v[70:71], v[66:67]
	global_store_dwordx4 v[130:131], v[64:67], off offset:448
	global_load_dwordx4 v[64:67], v[130:131], off offset:480
	s_nop 0
	global_load_dwordx4 v[68:71], v[132:133], off offset:480
	s_waitcnt vmcnt(0)
	v_pk_fma_f32 v[64:65], v[76:77], v[68:69], v[64:65]
	v_or_b32_e32 v68, 32, v134
	v_pk_fma_f32 v[66:67], v[78:79], v[70:71], v[66:67]
	v_cmp_lt_i32_e32 vcc, s57, v68
	global_store_dwordx4 v[130:131], v[64:67], off offset:480
	s_and_saveexec_b64 s[4:5], vcc
	s_xor_b64 s[4:5], exec, s[4:5]
	v_add_u32_e32 v190, 0xffffc020, v134
	v_mov_b64_e32 v[64:65], v[190:191]
	s_or_saveexec_b64 s[4:5], s[4:5]
	v_mov_b32_e32 v69, 0
	v_mov_b64_e32 v[66:67], 0
	s_xor_b64 exec, exec, s[4:5]
	s_cbranch_execz .LBB0_1118
	v_add_u32_e32 v64, s21, v68
	v_ashrrev_i32_e32 v65, 12, v64
	v_add_u32_e32 v69, 1, v65
	v_ashrrev_i32_e32 v65, 31, v64
	v_mov_b64_e32 v[66:67], 0x400000
	s_branch .LBB0_1118
